# speedup vs baseline: 1.0055x; 1.0017x over previous
; __device__ __forceinline__ void dsa_tile(const Params& p, unsigned char* smem, int tile) {
;     ...
;                     for (int r = g * 16; r < g * 16 + 16; ++r) {
;                         const bool sel = uu[r] > tau;
;                         const unsigned long long mk = __ballot(sel);
;                         const int pos = base + __builtin_amdgcn_mbcnt_hi((unsigned)(mk >> 32), __builtin_amdgcn_mbcnt_lo((unsigned)mk, 0));
;                         if (sel) myidx[pos] = r * 64 + lo;
;                         base += __popcll(mk);
;                         const unsigned long long me = __ballot(uu[r] == tau);
;                         if (me != 0ull) {
;                             const int epos = ebase + __builtin_amdgcn_mbcnt_hi((unsigned)(me >> 32), __builtin_amdgcn_mbcnt_lo((unsigned)me, 0));
;                             if (uu[r] == tau && epos < 256) myidx[epos] = r * 64 + lo;
;                             ebase += __popcll(me);
;                         }
.LBB0_887:
	v_lshlrev_b32_e32 v0, 2, v1
	s_bcnt1_i32_b64 s28, s[22:23]
	v_cmpx_lt_u32_e64 s[22:23], s26, v128
	s_nop 1
	s_lshl_b32 s4, s28, 2
	v_mbcnt_lo_u32_b32 v131, s22, 0
	s_add_i32 s4, s96, s4
	v_mbcnt_hi_u32_b32 v131, s23, v131
	v_add_u32_e32 v130, 64, v129
	v_lshl_add_u32 v131, v131, 2, s4
	ds_write_b32 v131, v130
.LBB0_889:
	s_mov_b64 exec, -1
	v_cmp_eq_u32_e32 vcc, s26, v128
	s_cbranch_vccz .LBB0_893
	s_nop 0
	v_mbcnt_lo_u32_b32 v128, vcc_lo, 0
	v_mbcnt_hi_u32_b32 v128, vcc_hi, v128
	v_add_u32_e32 v128, s27, v128
	v_cmp_gt_i32_e64 s[24:25], s78, v128
	s_and_b64 s[4:5], vcc, s[24:25]
	s_and_saveexec_b64 s[24:25], s[4:5]
	v_add_u32_e32 v130, 64, v129
	v_lshl_add_u32 v128, v128, 2, s96
	ds_write_b32 v128, v130
	s_or_b64 exec, exec, s[24:25]
	s_bcnt1_i32_b64 s4, vcc
	s_add_i32 s27, s27, s4
.LBB0_893:
	s_bcnt1_i32_b64 s4, s[22:23]
	s_add_i32 s28, s4, s28
	v_cmpx_lt_u32_e64 s[22:23], s26, v127
	s_nop 1
	s_lshl_b32 s4, s28, 2
	v_mbcnt_lo_u32_b32 v130, s22, 0
	s_add_i32 s4, s96, s4
	v_mbcnt_hi_u32_b32 v130, s23, v130
	v_add_u32_e32 v128, 0x80, v129
	v_lshl_add_u32 v130, v130, 2, s4
	ds_write_b32 v130, v128
.LBB0_895:
	s_mov_b64 exec, -1
	v_cmp_eq_u32_e32 vcc, s26, v127
	s_cbranch_vccz .LBB0_899
	s_nop 0
	v_mbcnt_lo_u32_b32 v127, vcc_lo, 0
	v_mbcnt_hi_u32_b32 v127, vcc_hi, v127
	v_add_u32_e32 v127, s27, v127
	v_cmp_gt_i32_e64 s[24:25], s78, v127
	s_and_b64 s[4:5], vcc, s[24:25]
	s_and_saveexec_b64 s[24:25], s[4:5]
	v_add_u32_e32 v128, 0x80, v129
	v_lshl_add_u32 v127, v127, 2, s96
	ds_write_b32 v127, v128
	s_or_b64 exec, exec, s[24:25]
	s_bcnt1_i32_b64 s4, vcc
	s_add_i32 s27, s27, s4
.LBB0_899:
	s_bcnt1_i32_b64 s4, s[22:23]
	s_add_i32 s28, s28, s4
	v_cmpx_lt_u32_e64 s[22:23], s26, v126
	s_nop 1
	s_lshl_b32 s4, s28, 2
	v_mbcnt_lo_u32_b32 v128, s22, 0
	s_add_i32 s4, s96, s4
	v_mbcnt_hi_u32_b32 v128, s23, v128
	v_add_u32_e32 v127, 0xc0, v129
	v_lshl_add_u32 v128, v128, 2, s4
	ds_write_b32 v128, v127
.LBB0_901:
	s_mov_b64 exec, -1
	v_cmp_eq_u32_e32 vcc, s26, v126
	s_cbranch_vccz .LBB0_905
	s_nop 0
	v_mbcnt_lo_u32_b32 v126, vcc_lo, 0
	v_mbcnt_hi_u32_b32 v126, vcc_hi, v126
	v_add_u32_e32 v126, s27, v126
	v_cmp_gt_i32_e64 s[24:25], s78, v126
	s_and_b64 s[4:5], vcc, s[24:25]
	s_and_saveexec_b64 s[24:25], s[4:5]
	v_add_u32_e32 v127, 0xc0, v129
	v_lshl_add_u32 v126, v126, 2, s96
	ds_write_b32 v126, v127
	s_or_b64 exec, exec, s[24:25]
	s_bcnt1_i32_b64 s4, vcc
	s_add_i32 s27, s27, s4
.LBB0_905:
	s_bcnt1_i32_b64 s4, s[22:23]
	s_add_i32 s28, s28, s4
	v_cmpx_lt_u32_e64 s[22:23], s26, v125
	s_nop 1
	s_lshl_b32 s4, s28, 2
	v_mbcnt_lo_u32_b32 v127, s22, 0
	s_add_i32 s4, s96, s4
	v_mbcnt_hi_u32_b32 v127, s23, v127
	v_add_u32_e32 v126, 0x100, v129
	v_lshl_add_u32 v127, v127, 2, s4
	ds_write_b32 v127, v126
.LBB0_907:
	s_mov_b64 exec, -1
	v_cmp_eq_u32_e32 vcc, s26, v125
	s_cbranch_vccz .LBB0_911
	s_nop 0
	v_mbcnt_lo_u32_b32 v125, vcc_lo, 0
	v_mbcnt_hi_u32_b32 v125, vcc_hi, v125
	v_add_u32_e32 v125, s27, v125
	v_cmp_gt_i32_e64 s[24:25], s78, v125
	s_and_b64 s[4:5], vcc, s[24:25]
	s_and_saveexec_b64 s[24:25], s[4:5]
	v_add_u32_e32 v126, 0x100, v129
	v_lshl_add_u32 v125, v125, 2, s96
	ds_write_b32 v125, v126
	s_or_b64 exec, exec, s[24:25]
	s_bcnt1_i32_b64 s4, vcc
	s_add_i32 s27, s27, s4
.LBB0_911:
	s_bcnt1_i32_b64 s4, s[22:23]
	s_add_i32 s28, s28, s4
	v_cmpx_lt_u32_e64 s[22:23], s26, v124
	s_nop 1
	s_lshl_b32 s4, s28, 2
	v_mbcnt_lo_u32_b32 v126, s22, 0
	s_add_i32 s4, s96, s4
	v_mbcnt_hi_u32_b32 v126, s23, v126
	v_add_u32_e32 v125, 0x140, v129
	v_lshl_add_u32 v126, v126, 2, s4
	ds_write_b32 v126, v125
.LBB0_913:
	s_mov_b64 exec, -1
	v_cmp_eq_u32_e32 vcc, s26, v124
	s_cbranch_vccz .LBB0_917
	s_nop 0
	v_mbcnt_lo_u32_b32 v124, vcc_lo, 0
	v_mbcnt_hi_u32_b32 v124, vcc_hi, v124
	v_add_u32_e32 v124, s27, v124
	v_cmp_gt_i32_e64 s[24:25], s78, v124
	s_and_b64 s[4:5], vcc, s[24:25]
	s_and_saveexec_b64 s[24:25], s[4:5]
	v_add_u32_e32 v125, 0x140, v129
	v_lshl_add_u32 v124, v124, 2, s96
	ds_write_b32 v124, v125
	s_or_b64 exec, exec, s[24:25]
	s_bcnt1_i32_b64 s4, vcc
	s_add_i32 s27, s27, s4
.LBB0_917:
	s_bcnt1_i32_b64 s4, s[22:23]
	s_add_i32 s28, s28, s4
	v_cmpx_lt_u32_e64 s[22:23], s26, v123
	s_nop 1
	s_lshl_b32 s4, s28, 2
	v_mbcnt_lo_u32_b32 v125, s22, 0
	s_add_i32 s4, s96, s4
	v_mbcnt_hi_u32_b32 v125, s23, v125
	v_add_u32_e32 v124, 0x180, v129
	v_lshl_add_u32 v125, v125, 2, s4
	ds_write_b32 v125, v124
.LBB0_919:
	s_mov_b64 exec, -1
	v_cmp_eq_u32_e32 vcc, s26, v123
	s_cbranch_vccz .LBB0_923
	s_nop 0
	v_mbcnt_lo_u32_b32 v123, vcc_lo, 0
	v_mbcnt_hi_u32_b32 v123, vcc_hi, v123
	v_add_u32_e32 v123, s27, v123
	v_cmp_gt_i32_e64 s[24:25], s78, v123
	s_and_b64 s[4:5], vcc, s[24:25]
	s_and_saveexec_b64 s[24:25], s[4:5]
	v_add_u32_e32 v124, 0x180, v129
	v_lshl_add_u32 v123, v123, 2, s96
	ds_write_b32 v123, v124
	s_or_b64 exec, exec, s[24:25]
	s_bcnt1_i32_b64 s4, vcc
	s_add_i32 s27, s27, s4
.LBB0_923:
	s_bcnt1_i32_b64 s4, s[22:23]
	s_add_i32 s28, s28, s4
	v_cmpx_lt_u32_e64 s[22:23], s26, v122
	s_nop 1
	s_lshl_b32 s4, s28, 2
	v_mbcnt_lo_u32_b32 v124, s22, 0
	s_add_i32 s4, s96, s4
	v_mbcnt_hi_u32_b32 v124, s23, v124
	v_add_u32_e32 v123, 0x1c0, v129
	v_lshl_add_u32 v124, v124, 2, s4
	ds_write_b32 v124, v123
.LBB0_925:
	s_mov_b64 exec, -1
	v_cmp_eq_u32_e32 vcc, s26, v122
	s_cbranch_vccz .LBB0_929
	s_nop 0
	v_mbcnt_lo_u32_b32 v122, vcc_lo, 0
	v_mbcnt_hi_u32_b32 v122, vcc_hi, v122
	v_add_u32_e32 v122, s27, v122
	v_cmp_gt_i32_e64 s[24:25], s78, v122
	s_and_b64 s[4:5], vcc, s[24:25]
	s_and_saveexec_b64 s[24:25], s[4:5]
	v_add_u32_e32 v123, 0x1c0, v129
	v_lshl_add_u32 v122, v122, 2, s96
	ds_write_b32 v122, v123
	s_or_b64 exec, exec, s[24:25]
	s_bcnt1_i32_b64 s4, vcc
	s_add_i32 s27, s27, s4
; __device__ __forceinline__ void dsa_tile(const Params& p, unsigned char* smem, int tile) {
;     ...
;                     for (int r = g * 16; r < g * 16 + 16; ++r) {
;                         const bool sel = uu[r] > tau;
;                         const unsigned long long mk = __ballot(sel);
;                         const int pos = base + __builtin_amdgcn_mbcnt_hi((unsigned)(mk >> 32), __builtin_amdgcn_mbcnt_lo((unsigned)mk, 0));
;                         if (sel) myidx[pos] = r * 64 + lo;
;                         base += __popcll(mk);
;                         const unsigned long long me = __ballot(uu[r] == tau);
;                         if (me != 0ull) {
;                             const int epos = ebase + __builtin_amdgcn_mbcnt_hi((unsigned)(me >> 32), __builtin_amdgcn_mbcnt_lo((unsigned)me, 0));
;                             if (uu[r] == tau && epos < 256) myidx[epos] = r * 64 + lo;
;                             ebase += __popcll(me);
;                         }
.LBB0_929:
	s_bcnt1_i32_b64 s4, s[22:23]
	s_add_i32 s28, s28, s4
	v_cmpx_lt_u32_e64 s[22:23], s26, v121
	s_nop 1
	s_lshl_b32 s4, s28, 2
	v_mbcnt_lo_u32_b32 v123, s22, 0
	s_add_i32 s4, s96, s4
	v_mbcnt_hi_u32_b32 v123, s23, v123
	v_add_u32_e32 v122, 0x200, v129
	v_lshl_add_u32 v123, v123, 2, s4
	ds_write_b32 v123, v122
.LBB0_931:
	s_mov_b64 exec, -1
	v_cmp_eq_u32_e32 vcc, s26, v121
	s_cbranch_vccz .LBB0_935
	s_nop 0
	v_mbcnt_lo_u32_b32 v121, vcc_lo, 0
	v_mbcnt_hi_u32_b32 v121, vcc_hi, v121
	v_add_u32_e32 v121, s27, v121
	v_cmp_gt_i32_e64 s[24:25], s78, v121
	s_and_b64 s[4:5], vcc, s[24:25]
	s_and_saveexec_b64 s[24:25], s[4:5]
	v_add_u32_e32 v122, 0x200, v129
	v_lshl_add_u32 v121, v121, 2, s96
	ds_write_b32 v121, v122
	s_or_b64 exec, exec, s[24:25]
	s_bcnt1_i32_b64 s4, vcc
	s_add_i32 s27, s27, s4
.LBB0_935:
	s_bcnt1_i32_b64 s4, s[22:23]
	s_add_i32 s28, s28, s4
	v_cmpx_lt_u32_e64 s[22:23], s26, v120
	s_nop 1
	s_lshl_b32 s4, s28, 2
	v_mbcnt_lo_u32_b32 v122, s22, 0
	s_add_i32 s4, s96, s4
	v_mbcnt_hi_u32_b32 v122, s23, v122
	v_add_u32_e32 v121, 0x240, v129
	v_lshl_add_u32 v122, v122, 2, s4
	ds_write_b32 v122, v121
.LBB0_937:
	s_mov_b64 exec, -1
	v_cmp_eq_u32_e32 vcc, s26, v120
	s_cbranch_vccz .LBB0_941
	s_nop 0
	v_mbcnt_lo_u32_b32 v120, vcc_lo, 0
	v_mbcnt_hi_u32_b32 v120, vcc_hi, v120
	v_add_u32_e32 v120, s27, v120
	v_cmp_gt_i32_e64 s[24:25], s78, v120
	s_and_b64 s[4:5], vcc, s[24:25]
	s_and_saveexec_b64 s[24:25], s[4:5]
	v_add_u32_e32 v121, 0x240, v129
	v_lshl_add_u32 v120, v120, 2, s96
	ds_write_b32 v120, v121
	s_or_b64 exec, exec, s[24:25]
	s_bcnt1_i32_b64 s4, vcc
	s_add_i32 s27, s27, s4
.LBB0_941:
	s_bcnt1_i32_b64 s4, s[22:23]
	s_add_i32 s28, s28, s4
	v_cmpx_lt_u32_e64 s[22:23], s26, v119
	s_nop 1
	s_lshl_b32 s4, s28, 2
	v_mbcnt_lo_u32_b32 v121, s22, 0
	s_add_i32 s4, s96, s4
	v_mbcnt_hi_u32_b32 v121, s23, v121
	v_add_u32_e32 v120, 0x280, v129
	v_lshl_add_u32 v121, v121, 2, s4
	ds_write_b32 v121, v120
.LBB0_943:
	s_mov_b64 exec, -1
	v_cmp_eq_u32_e32 vcc, s26, v119
	s_cbranch_vccz .LBB0_947
	s_nop 0
	v_mbcnt_lo_u32_b32 v119, vcc_lo, 0
	v_mbcnt_hi_u32_b32 v119, vcc_hi, v119
	v_add_u32_e32 v119, s27, v119
	v_cmp_gt_i32_e64 s[24:25], s78, v119
	s_and_b64 s[4:5], vcc, s[24:25]
	s_and_saveexec_b64 s[24:25], s[4:5]
	v_add_u32_e32 v120, 0x280, v129
	v_lshl_add_u32 v119, v119, 2, s96
	ds_write_b32 v119, v120
	s_or_b64 exec, exec, s[24:25]
	s_bcnt1_i32_b64 s4, vcc
	s_add_i32 s27, s27, s4
.LBB0_947:
	s_bcnt1_i32_b64 s4, s[22:23]
	s_add_i32 s28, s28, s4
	v_cmpx_lt_u32_e64 s[22:23], s26, v118
	s_nop 1
	s_lshl_b32 s4, s28, 2
	v_mbcnt_lo_u32_b32 v120, s22, 0
	s_add_i32 s4, s96, s4
	v_mbcnt_hi_u32_b32 v120, s23, v120
	v_add_u32_e32 v119, 0x2c0, v129
	v_lshl_add_u32 v120, v120, 2, s4
	ds_write_b32 v120, v119
.LBB0_949:
	s_mov_b64 exec, -1
	v_cmp_eq_u32_e32 vcc, s26, v118
	s_cbranch_vccz .LBB0_953
	s_nop 0
	v_mbcnt_lo_u32_b32 v118, vcc_lo, 0
	v_mbcnt_hi_u32_b32 v118, vcc_hi, v118
	v_add_u32_e32 v118, s27, v118
	v_cmp_gt_i32_e64 s[24:25], s78, v118
	s_and_b64 s[4:5], vcc, s[24:25]
	s_and_saveexec_b64 s[24:25], s[4:5]
	v_add_u32_e32 v119, 0x2c0, v129
	v_lshl_add_u32 v118, v118, 2, s96
	ds_write_b32 v118, v119
	s_or_b64 exec, exec, s[24:25]
	s_bcnt1_i32_b64 s4, vcc
	s_add_i32 s27, s27, s4
.LBB0_953:
	s_bcnt1_i32_b64 s4, s[22:23]
	s_add_i32 s28, s28, s4
	v_cmpx_lt_u32_e64 s[22:23], s26, v117
	s_nop 1
	s_lshl_b32 s4, s28, 2
	v_mbcnt_lo_u32_b32 v119, s22, 0
	s_add_i32 s4, s96, s4
	v_mbcnt_hi_u32_b32 v119, s23, v119
	v_add_u32_e32 v118, 0x300, v129
	v_lshl_add_u32 v119, v119, 2, s4
	ds_write_b32 v119, v118
.LBB0_955:
	s_mov_b64 exec, -1
	v_cmp_eq_u32_e32 vcc, s26, v117
	s_cbranch_vccz .LBB0_959
	s_nop 0
	v_mbcnt_lo_u32_b32 v117, vcc_lo, 0
	v_mbcnt_hi_u32_b32 v117, vcc_hi, v117
	v_add_u32_e32 v117, s27, v117
	v_cmp_gt_i32_e64 s[24:25], s78, v117
	s_and_b64 s[4:5], vcc, s[24:25]
	s_and_saveexec_b64 s[24:25], s[4:5]
	v_add_u32_e32 v118, 0x300, v129
	v_lshl_add_u32 v117, v117, 2, s96
	ds_write_b32 v117, v118
	s_or_b64 exec, exec, s[24:25]
	s_bcnt1_i32_b64 s4, vcc
	s_add_i32 s27, s27, s4
.LBB0_959:
	s_bcnt1_i32_b64 s4, s[22:23]
	s_add_i32 s28, s28, s4
	v_cmpx_lt_u32_e64 s[22:23], s26, v116
	s_nop 1
	s_lshl_b32 s4, s28, 2
	v_mbcnt_lo_u32_b32 v118, s22, 0
	s_add_i32 s4, s96, s4
	v_mbcnt_hi_u32_b32 v118, s23, v118
	v_add_u32_e32 v117, 0x340, v129
	v_lshl_add_u32 v118, v118, 2, s4
	ds_write_b32 v118, v117
.LBB0_961:
	s_mov_b64 exec, -1
	v_cmp_eq_u32_e32 vcc, s26, v116
	s_cbranch_vccz .LBB0_965
	s_nop 0
	v_mbcnt_lo_u32_b32 v116, vcc_lo, 0
	v_mbcnt_hi_u32_b32 v116, vcc_hi, v116
	v_add_u32_e32 v116, s27, v116
	v_cmp_gt_i32_e64 s[24:25], s78, v116
	s_and_b64 s[4:5], vcc, s[24:25]
	s_and_saveexec_b64 s[24:25], s[4:5]
	v_add_u32_e32 v117, 0x340, v129
	v_lshl_add_u32 v116, v116, 2, s96
	ds_write_b32 v116, v117
	s_or_b64 exec, exec, s[24:25]
	s_bcnt1_i32_b64 s4, vcc
	s_add_i32 s27, s27, s4
.LBB0_965:
	s_bcnt1_i32_b64 s4, s[22:23]
	s_add_i32 s28, s28, s4
	v_cmpx_lt_u32_e64 s[22:23], s26, v115
	s_nop 1
	s_lshl_b32 s4, s28, 2
	v_mbcnt_lo_u32_b32 v117, s22, 0
	s_add_i32 s4, s96, s4
	v_mbcnt_hi_u32_b32 v117, s23, v117
	v_add_u32_e32 v116, 0x380, v129
	v_lshl_add_u32 v117, v117, 2, s4
	ds_write_b32 v117, v116
.LBB0_967:
	s_mov_b64 exec, -1
	v_cmp_eq_u32_e32 vcc, s26, v115
	s_cbranch_vccz .LBB0_971
	s_nop 0
	v_mbcnt_lo_u32_b32 v115, vcc_lo, 0
	v_mbcnt_hi_u32_b32 v115, vcc_hi, v115
	v_add_u32_e32 v115, s27, v115
	v_cmp_gt_i32_e64 s[24:25], s78, v115
	s_and_b64 s[4:5], vcc, s[24:25]
	s_and_saveexec_b64 s[24:25], s[4:5]
	v_add_u32_e32 v116, 0x380, v129
	v_lshl_add_u32 v115, v115, 2, s96
	ds_write_b32 v115, v116
	s_or_b64 exec, exec, s[24:25]
	s_bcnt1_i32_b64 s4, vcc
	s_add_i32 s27, s27, s4
.LBB0_971:
	s_bcnt1_i32_b64 s4, s[22:23]
	s_add_i32 s28, s28, s4
	v_cmpx_lt_u32_e64 s[22:23], s26, v114
	s_nop 1
	s_lshl_b32 s4, s28, 2
	v_mbcnt_lo_u32_b32 v116, s22, 0
	s_add_i32 s4, s96, s4
	v_mbcnt_hi_u32_b32 v116, s23, v116
	v_add_u32_e32 v115, 0x3c0, v129
	v_lshl_add_u32 v116, v116, 2, s4
	ds_write_b32 v116, v115
.LBB0_973:
	s_mov_b64 exec, -1
	v_cmp_eq_u32_e32 vcc, s26, v114
	s_cbranch_vccz .LBB0_977
	s_nop 0
	v_mbcnt_lo_u32_b32 v114, vcc_lo, 0
	v_mbcnt_hi_u32_b32 v114, vcc_hi, v114
	v_add_u32_e32 v114, s27, v114
	v_cmp_gt_i32_e64 s[24:25], s78, v114
	s_and_b64 s[4:5], vcc, s[24:25]
	s_and_saveexec_b64 s[24:25], s[4:5]
	v_add_u32_e32 v115, 0x3c0, v129
	v_lshl_add_u32 v114, v114, 2, s96
	ds_write_b32 v114, v115
	s_or_b64 exec, exec, s[24:25]
	s_bcnt1_i32_b64 s4, vcc
	s_add_i32 s27, s27, s4

; __device__ __forceinline__ void dsa_tile(const Params& p, unsigned char* smem, int tile) {
;     ...
;                     for (int r = g * 16; r < g * 16 + 16; ++r) {
;                         const bool sel = uu[r] > tau;
;                         const unsigned long long mk = __ballot(sel);
;                         const int pos = base + __builtin_amdgcn_mbcnt_hi((unsigned)(mk >> 32), __builtin_amdgcn_mbcnt_lo((unsigned)mk, 0));
;                         if (sel) myidx[pos] = r * 64 + lo;
;                         base += __popcll(mk);
;                         const unsigned long long me = __ballot(uu[r] == tau);
;                         if (me != 0ull) {
;                             const int epos = ebase + __builtin_amdgcn_mbcnt_hi((unsigned)(me >> 32), __builtin_amdgcn_mbcnt_lo((unsigned)me, 0));
;                             if (uu[r] == tau && epos < 256) myidx[epos] = r * 64 + lo;
;                             ebase += __popcll(me);
;                         }
.LBB0_990:
	s_bcnt1_i32_b64 s4, s[20:21]
	s_add_i32 s24, s24, s4
	v_cmpx_lt_u32_e64 s[20:21], s26, v112
	s_nop 1
	s_lshl_b32 s4, s24, 2
	v_mbcnt_lo_u32_b32 v115, s20, 0
	s_add_i32 s4, s96, s4
	v_mbcnt_hi_u32_b32 v115, s21, v115
	v_add_u32_e32 v113, 0x440, v114
	v_lshl_add_u32 v115, v115, 2, s4
	ds_write_b32 v115, v113
.LBB0_992:
	s_mov_b64 exec, -1
	v_cmp_eq_u32_e32 vcc, s26, v112
	s_cbranch_vccz .LBB0_996
	s_nop 0
	v_mbcnt_lo_u32_b32 v112, vcc_lo, 0
	v_mbcnt_hi_u32_b32 v112, vcc_hi, v112
	v_add_u32_e32 v112, s27, v112
	v_cmp_gt_i32_e64 s[22:23], s78, v112
	s_and_b64 s[4:5], vcc, s[22:23]
	s_and_saveexec_b64 s[22:23], s[4:5]
	v_add_u32_e32 v113, 0x440, v114
	v_lshl_add_u32 v112, v112, 2, s96
	ds_write_b32 v112, v113
	s_or_b64 exec, exec, s[22:23]
	s_bcnt1_i32_b64 s4, vcc
	s_add_i32 s27, s27, s4
.LBB0_996:
	s_bcnt1_i32_b64 s4, s[20:21]
	s_add_i32 s24, s24, s4
	v_cmpx_lt_u32_e64 s[20:21], s26, v111
	s_nop 1
	s_lshl_b32 s4, s24, 2
	v_mbcnt_lo_u32_b32 v113, s20, 0
	s_add_i32 s4, s96, s4
	v_mbcnt_hi_u32_b32 v113, s21, v113
	v_add_u32_e32 v112, 0x480, v114
	v_lshl_add_u32 v113, v113, 2, s4
	ds_write_b32 v113, v112
.LBB0_998:
	s_mov_b64 exec, -1
	v_cmp_eq_u32_e32 vcc, s26, v111
	s_cbranch_vccz .LBB0_1002
	s_nop 0
	v_mbcnt_lo_u32_b32 v111, vcc_lo, 0
	v_mbcnt_hi_u32_b32 v111, vcc_hi, v111
	v_add_u32_e32 v111, s27, v111
	v_cmp_gt_i32_e64 s[22:23], s78, v111
	s_and_b64 s[4:5], vcc, s[22:23]
	s_and_saveexec_b64 s[22:23], s[4:5]
	v_add_u32_e32 v112, 0x480, v114
	v_lshl_add_u32 v111, v111, 2, s96
	ds_write_b32 v111, v112
	s_or_b64 exec, exec, s[22:23]
	s_bcnt1_i32_b64 s4, vcc
	s_add_i32 s27, s27, s4
.LBB0_1002:
	s_bcnt1_i32_b64 s4, s[20:21]
	s_add_i32 s24, s24, s4
	v_cmpx_lt_u32_e64 s[20:21], s26, v110
	s_nop 1
	s_lshl_b32 s4, s24, 2
	v_mbcnt_lo_u32_b32 v112, s20, 0
	s_add_i32 s4, s96, s4
	v_mbcnt_hi_u32_b32 v112, s21, v112
	v_add_u32_e32 v111, 0x4c0, v114
	v_lshl_add_u32 v112, v112, 2, s4
	ds_write_b32 v112, v111
.LBB0_1004:
	s_mov_b64 exec, -1
	v_cmp_eq_u32_e32 vcc, s26, v110
	s_cbranch_vccz .LBB0_1008
	s_nop 0
	v_mbcnt_lo_u32_b32 v110, vcc_lo, 0
	v_mbcnt_hi_u32_b32 v110, vcc_hi, v110
	v_add_u32_e32 v110, s27, v110
	v_cmp_gt_i32_e64 s[22:23], s78, v110
	s_and_b64 s[4:5], vcc, s[22:23]
	s_and_saveexec_b64 s[22:23], s[4:5]
	v_add_u32_e32 v111, 0x4c0, v114
	v_lshl_add_u32 v110, v110, 2, s96
	ds_write_b32 v110, v111
	s_or_b64 exec, exec, s[22:23]
	s_bcnt1_i32_b64 s4, vcc
	s_add_i32 s27, s27, s4
.LBB0_1008:
	s_bcnt1_i32_b64 s4, s[20:21]
	s_add_i32 s24, s24, s4
	v_cmpx_lt_u32_e64 s[20:21], s26, v109
	s_nop 1
	s_lshl_b32 s4, s24, 2
	v_mbcnt_lo_u32_b32 v111, s20, 0
	s_add_i32 s4, s96, s4
	v_mbcnt_hi_u32_b32 v111, s21, v111
	v_add_u32_e32 v110, 0x500, v114
	v_lshl_add_u32 v111, v111, 2, s4
	ds_write_b32 v111, v110
.LBB0_1010:
	s_mov_b64 exec, -1
	v_cmp_eq_u32_e32 vcc, s26, v109
	s_cbranch_vccz .LBB0_1014
	s_nop 0
	v_mbcnt_lo_u32_b32 v109, vcc_lo, 0
	v_mbcnt_hi_u32_b32 v109, vcc_hi, v109
	v_add_u32_e32 v109, s27, v109
	v_cmp_gt_i32_e64 s[22:23], s78, v109
	s_and_b64 s[4:5], vcc, s[22:23]
	s_and_saveexec_b64 s[22:23], s[4:5]
	v_add_u32_e32 v110, 0x500, v114
	v_lshl_add_u32 v109, v109, 2, s96
	ds_write_b32 v109, v110
	s_or_b64 exec, exec, s[22:23]
	s_bcnt1_i32_b64 s4, vcc
	s_add_i32 s27, s27, s4
.LBB0_1014:
	s_bcnt1_i32_b64 s4, s[20:21]
	s_add_i32 s24, s24, s4
	v_cmpx_lt_u32_e64 s[20:21], s26, v108
	s_nop 1
	s_lshl_b32 s4, s24, 2
	v_mbcnt_lo_u32_b32 v110, s20, 0
	s_add_i32 s4, s96, s4
	v_mbcnt_hi_u32_b32 v110, s21, v110
	v_add_u32_e32 v109, 0x540, v114
	v_lshl_add_u32 v110, v110, 2, s4
	ds_write_b32 v110, v109
.LBB0_1016:
	s_mov_b64 exec, -1
	v_cmp_eq_u32_e32 vcc, s26, v108
	s_cbranch_vccz .LBB0_1020
	s_nop 0
	v_mbcnt_lo_u32_b32 v108, vcc_lo, 0
	v_mbcnt_hi_u32_b32 v108, vcc_hi, v108
	v_add_u32_e32 v108, s27, v108
	v_cmp_gt_i32_e64 s[22:23], s78, v108
	s_and_b64 s[4:5], vcc, s[22:23]
	s_and_saveexec_b64 s[22:23], s[4:5]
	v_add_u32_e32 v109, 0x540, v114
	v_lshl_add_u32 v108, v108, 2, s96
	ds_write_b32 v108, v109
	s_or_b64 exec, exec, s[22:23]
	s_bcnt1_i32_b64 s4, vcc
	s_add_i32 s27, s27, s4
.LBB0_1020:
	s_bcnt1_i32_b64 s4, s[20:21]
	s_add_i32 s24, s24, s4
	v_cmpx_lt_u32_e64 s[20:21], s26, v107
	s_nop 1
	s_lshl_b32 s4, s24, 2
	v_mbcnt_lo_u32_b32 v109, s20, 0
	s_add_i32 s4, s96, s4
	v_mbcnt_hi_u32_b32 v109, s21, v109
	v_add_u32_e32 v108, 0x580, v114
	v_lshl_add_u32 v109, v109, 2, s4
	ds_write_b32 v109, v108
.LBB0_1022:
	s_mov_b64 exec, -1
	v_cmp_eq_u32_e32 vcc, s26, v107
	s_cbranch_vccz .LBB0_1026
	s_nop 0
	v_mbcnt_lo_u32_b32 v107, vcc_lo, 0
	v_mbcnt_hi_u32_b32 v107, vcc_hi, v107
	v_add_u32_e32 v107, s27, v107
	v_cmp_gt_i32_e64 s[22:23], s78, v107
	s_and_b64 s[4:5], vcc, s[22:23]
	s_and_saveexec_b64 s[22:23], s[4:5]
	v_add_u32_e32 v108, 0x580, v114
	v_lshl_add_u32 v107, v107, 2, s96
	ds_write_b32 v107, v108
	s_or_b64 exec, exec, s[22:23]
	s_bcnt1_i32_b64 s4, vcc
	s_add_i32 s27, s27, s4
.LBB0_1026:
	s_bcnt1_i32_b64 s4, s[20:21]
	s_add_i32 s24, s24, s4
	v_cmpx_lt_u32_e64 s[20:21], s26, v106
	s_nop 1
	s_lshl_b32 s4, s24, 2
	v_mbcnt_lo_u32_b32 v108, s20, 0
	s_add_i32 s4, s96, s4
	v_mbcnt_hi_u32_b32 v108, s21, v108
	v_add_u32_e32 v107, 0x5c0, v114
	v_lshl_add_u32 v108, v108, 2, s4
	ds_write_b32 v108, v107
.LBB0_1028:
	s_mov_b64 exec, -1
	v_cmp_eq_u32_e32 vcc, s26, v106
	s_cbranch_vccz .LBB0_1032
	s_nop 0
	v_mbcnt_lo_u32_b32 v106, vcc_lo, 0
	v_mbcnt_hi_u32_b32 v106, vcc_hi, v106
	v_add_u32_e32 v106, s27, v106
	v_cmp_gt_i32_e64 s[22:23], s78, v106
	s_and_b64 s[4:5], vcc, s[22:23]
	s_and_saveexec_b64 s[22:23], s[4:5]
	v_add_u32_e32 v107, 0x5c0, v114
	v_lshl_add_u32 v106, v106, 2, s96
	ds_write_b32 v106, v107
	s_or_b64 exec, exec, s[22:23]
	s_bcnt1_i32_b64 s4, vcc
	s_add_i32 s27, s27, s4
; __device__ __forceinline__ void dsa_tile(const Params& p, unsigned char* smem, int tile) {
;     ...
;                     for (int r = g * 16; r < g * 16 + 16; ++r) {
;                         const bool sel = uu[r] > tau;
;                         const unsigned long long mk = __ballot(sel);
;                         const int pos = base + __builtin_amdgcn_mbcnt_hi((unsigned)(mk >> 32), __builtin_amdgcn_mbcnt_lo((unsigned)mk, 0));
;                         if (sel) myidx[pos] = r * 64 + lo;
;                         base += __popcll(mk);
;                         const unsigned long long me = __ballot(uu[r] == tau);
;                         if (me != 0ull) {
;                             const int epos = ebase + __builtin_amdgcn_mbcnt_hi((unsigned)(me >> 32), __builtin_amdgcn_mbcnt_lo((unsigned)me, 0));
;                             if (uu[r] == tau && epos < 256) myidx[epos] = r * 64 + lo;
;                             ebase += __popcll(me);
;                         }
.LBB0_1032:
	s_bcnt1_i32_b64 s4, s[20:21]
	s_add_i32 s24, s24, s4
	v_cmpx_lt_u32_e64 s[20:21], s26, v105
	s_nop 1
	s_lshl_b32 s4, s24, 2
	v_mbcnt_lo_u32_b32 v107, s20, 0
	s_add_i32 s4, s96, s4
	v_mbcnt_hi_u32_b32 v107, s21, v107
	v_add_u32_e32 v106, 0x600, v114
	v_lshl_add_u32 v107, v107, 2, s4
	ds_write_b32 v107, v106
.LBB0_1034:
	s_mov_b64 exec, -1
	v_cmp_eq_u32_e32 vcc, s26, v105
	s_cbranch_vccz .LBB0_1038
	s_nop 0
	v_mbcnt_lo_u32_b32 v105, vcc_lo, 0
	v_mbcnt_hi_u32_b32 v105, vcc_hi, v105
	v_add_u32_e32 v105, s27, v105
	v_cmp_gt_i32_e64 s[22:23], s78, v105
	s_and_b64 s[4:5], vcc, s[22:23]
	s_and_saveexec_b64 s[22:23], s[4:5]
	v_add_u32_e32 v106, 0x600, v114
	v_lshl_add_u32 v105, v105, 2, s96
	ds_write_b32 v105, v106
	s_or_b64 exec, exec, s[22:23]
	s_bcnt1_i32_b64 s4, vcc
	s_add_i32 s27, s27, s4
.LBB0_1038:
	s_bcnt1_i32_b64 s4, s[20:21]
	s_add_i32 s24, s24, s4
	v_cmpx_lt_u32_e64 s[20:21], s26, v104
	s_nop 1
	s_lshl_b32 s4, s24, 2
	v_mbcnt_lo_u32_b32 v106, s20, 0
	s_add_i32 s4, s96, s4
	v_mbcnt_hi_u32_b32 v106, s21, v106
	v_add_u32_e32 v105, 0x640, v114
	v_lshl_add_u32 v106, v106, 2, s4
	ds_write_b32 v106, v105
.LBB0_1040:
	s_mov_b64 exec, -1
	v_cmp_eq_u32_e32 vcc, s26, v104
	s_cbranch_vccz .LBB0_1044
	s_nop 0
	v_mbcnt_lo_u32_b32 v104, vcc_lo, 0
	v_mbcnt_hi_u32_b32 v104, vcc_hi, v104
	v_add_u32_e32 v104, s27, v104
	v_cmp_gt_i32_e64 s[22:23], s78, v104
	s_and_b64 s[4:5], vcc, s[22:23]
	s_and_saveexec_b64 s[22:23], s[4:5]
	v_add_u32_e32 v105, 0x640, v114
	v_lshl_add_u32 v104, v104, 2, s96
	ds_write_b32 v104, v105
	s_or_b64 exec, exec, s[22:23]
	s_bcnt1_i32_b64 s4, vcc
	s_add_i32 s27, s27, s4
.LBB0_1044:
	s_bcnt1_i32_b64 s4, s[20:21]
	s_add_i32 s24, s24, s4
	v_cmpx_lt_u32_e64 s[20:21], s26, v103
	s_nop 1
	s_lshl_b32 s4, s24, 2
	v_mbcnt_lo_u32_b32 v105, s20, 0
	s_add_i32 s4, s96, s4
	v_mbcnt_hi_u32_b32 v105, s21, v105
	v_add_u32_e32 v104, 0x680, v114
	v_lshl_add_u32 v105, v105, 2, s4
	ds_write_b32 v105, v104
.LBB0_1046:
	s_mov_b64 exec, -1
	v_cmp_eq_u32_e32 vcc, s26, v103
	s_cbranch_vccz .LBB0_1050
	s_nop 0
	v_mbcnt_lo_u32_b32 v103, vcc_lo, 0
	v_mbcnt_hi_u32_b32 v103, vcc_hi, v103
	v_add_u32_e32 v103, s27, v103
	v_cmp_gt_i32_e64 s[22:23], s78, v103
	s_and_b64 s[4:5], vcc, s[22:23]
	s_and_saveexec_b64 s[22:23], s[4:5]
	v_add_u32_e32 v104, 0x680, v114
	v_lshl_add_u32 v103, v103, 2, s96
	ds_write_b32 v103, v104
	s_or_b64 exec, exec, s[22:23]
	s_bcnt1_i32_b64 s4, vcc
	s_add_i32 s27, s27, s4
.LBB0_1050:
	s_bcnt1_i32_b64 s4, s[20:21]
	s_add_i32 s24, s24, s4
	v_cmpx_lt_u32_e64 s[20:21], s26, v102
	s_nop 1
	s_lshl_b32 s4, s24, 2
	v_mbcnt_lo_u32_b32 v104, s20, 0
	s_add_i32 s4, s96, s4
	v_mbcnt_hi_u32_b32 v104, s21, v104
	v_add_u32_e32 v103, 0x6c0, v114
	v_lshl_add_u32 v104, v104, 2, s4
	ds_write_b32 v104, v103
.LBB0_1052:
	s_mov_b64 exec, -1
	v_cmp_eq_u32_e32 vcc, s26, v102
	s_cbranch_vccz .LBB0_1056
	s_nop 0
	v_mbcnt_lo_u32_b32 v102, vcc_lo, 0
	v_mbcnt_hi_u32_b32 v102, vcc_hi, v102
	v_add_u32_e32 v102, s27, v102
	v_cmp_gt_i32_e64 s[22:23], s78, v102
	s_and_b64 s[4:5], vcc, s[22:23]
	s_and_saveexec_b64 s[22:23], s[4:5]
	v_add_u32_e32 v103, 0x6c0, v114
	v_lshl_add_u32 v102, v102, 2, s96
	ds_write_b32 v102, v103
	s_or_b64 exec, exec, s[22:23]
	s_bcnt1_i32_b64 s4, vcc
	s_add_i32 s27, s27, s4
.LBB0_1056:
	s_bcnt1_i32_b64 s4, s[20:21]
	s_add_i32 s24, s24, s4
	v_cmpx_lt_u32_e64 s[20:21], s26, v101
	s_nop 1
	s_lshl_b32 s4, s24, 2
	v_mbcnt_lo_u32_b32 v103, s20, 0
	s_add_i32 s4, s96, s4
	v_mbcnt_hi_u32_b32 v103, s21, v103
	v_add_u32_e32 v102, 0x700, v114
	v_lshl_add_u32 v103, v103, 2, s4
	ds_write_b32 v103, v102
.LBB0_1058:
	s_mov_b64 exec, -1
	v_cmp_eq_u32_e32 vcc, s26, v101
	s_cbranch_vccz .LBB0_1062
	s_nop 0
	v_mbcnt_lo_u32_b32 v101, vcc_lo, 0
	v_mbcnt_hi_u32_b32 v101, vcc_hi, v101
	v_add_u32_e32 v101, s27, v101
	v_cmp_gt_i32_e64 s[22:23], s78, v101
	s_and_b64 s[4:5], vcc, s[22:23]
	s_and_saveexec_b64 s[22:23], s[4:5]
	v_add_u32_e32 v102, 0x700, v114
	v_lshl_add_u32 v101, v101, 2, s96
	ds_write_b32 v101, v102
	s_or_b64 exec, exec, s[22:23]
	s_bcnt1_i32_b64 s4, vcc
	s_add_i32 s27, s27, s4
.LBB0_1062:
	s_bcnt1_i32_b64 s4, s[20:21]
	s_add_i32 s24, s24, s4
	v_cmpx_lt_u32_e64 s[20:21], s26, v100
	s_nop 1
	s_lshl_b32 s4, s24, 2
	v_mbcnt_lo_u32_b32 v102, s20, 0
	s_add_i32 s4, s96, s4
	v_mbcnt_hi_u32_b32 v102, s21, v102
	v_add_u32_e32 v101, 0x740, v114
	v_lshl_add_u32 v102, v102, 2, s4
	ds_write_b32 v102, v101
.LBB0_1064:
	s_mov_b64 exec, -1
	v_cmp_eq_u32_e32 vcc, s26, v100
	s_cbranch_vccz .LBB0_1068
	s_nop 0
	v_mbcnt_lo_u32_b32 v100, vcc_lo, 0
	v_mbcnt_hi_u32_b32 v100, vcc_hi, v100
	v_add_u32_e32 v100, s27, v100
	v_cmp_gt_i32_e64 s[22:23], s78, v100
	s_and_b64 s[4:5], vcc, s[22:23]
	s_and_saveexec_b64 s[22:23], s[4:5]
	v_add_u32_e32 v101, 0x740, v114
	v_lshl_add_u32 v100, v100, 2, s96
	ds_write_b32 v100, v101
	s_or_b64 exec, exec, s[22:23]
	s_bcnt1_i32_b64 s4, vcc
	s_add_i32 s27, s27, s4
.LBB0_1068:
	s_bcnt1_i32_b64 s4, s[20:21]
	s_add_i32 s24, s24, s4
	v_cmpx_lt_u32_e64 s[20:21], s26, v99
	s_nop 1
	s_lshl_b32 s4, s24, 2
	v_mbcnt_lo_u32_b32 v101, s20, 0
	s_add_i32 s4, s96, s4
	v_mbcnt_hi_u32_b32 v101, s21, v101
	v_add_u32_e32 v100, 0x780, v114
	v_lshl_add_u32 v101, v101, 2, s4
	ds_write_b32 v101, v100
.LBB0_1070:
	s_mov_b64 exec, -1
	v_cmp_eq_u32_e32 vcc, s26, v99
	s_cbranch_vccz .LBB0_1074
	s_nop 0
	v_mbcnt_lo_u32_b32 v99, vcc_lo, 0
	v_mbcnt_hi_u32_b32 v99, vcc_hi, v99
	v_add_u32_e32 v99, s27, v99
	v_cmp_gt_i32_e64 s[22:23], s78, v99
	s_and_b64 s[4:5], vcc, s[22:23]
	s_and_saveexec_b64 s[22:23], s[4:5]
	v_add_u32_e32 v100, 0x780, v114
	v_lshl_add_u32 v99, v99, 2, s96
	ds_write_b32 v99, v100
	s_or_b64 exec, exec, s[22:23]
	s_bcnt1_i32_b64 s4, vcc
	s_add_i32 s27, s27, s4
.LBB0_1074:
	s_bcnt1_i32_b64 s4, s[20:21]
	s_add_i32 s24, s24, s4
	v_cmpx_lt_u32_e64 s[20:21], s26, v97
	s_nop 1
	s_lshl_b32 s4, s24, 2
	v_mbcnt_lo_u32_b32 v100, s20, 0
	s_add_i32 s4, s96, s4
	v_mbcnt_hi_u32_b32 v100, s21, v100
	v_add_u32_e32 v99, 0x7c0, v114
	v_lshl_add_u32 v100, v100, 2, s4
	ds_write_b32 v100, v99
.LBB0_1076:
	s_mov_b64 exec, -1
	v_cmp_eq_u32_e32 vcc, s26, v97
	s_cbranch_vccz .LBB0_1080
	s_nop 0
	v_mbcnt_lo_u32_b32 v97, vcc_lo, 0
	v_mbcnt_hi_u32_b32 v97, vcc_hi, v97
	v_add_u32_e32 v97, s27, v97
	v_cmp_gt_i32_e64 s[22:23], s78, v97
	s_and_b64 s[4:5], vcc, s[22:23]
	s_and_saveexec_b64 s[22:23], s[4:5]
	v_add_u32_e32 v99, 0x7c0, v114
	v_lshl_add_u32 v97, v97, 2, s96
	ds_write_b32 v97, v99
	s_or_b64 exec, exec, s[22:23]
	s_bcnt1_i32_b64 s4, vcc
	s_add_i32 s27, s27, s4

; __device__ __forceinline__ void dsa_tile(const Params& p, unsigned char* smem, int tile) {
;     ...
;                     for (int r = g * 16; r < g * 16 + 16; ++r) {
;                         const bool sel = uu[r] > tau;
;                         const unsigned long long mk = __ballot(sel);
;                         const int pos = base + __builtin_amdgcn_mbcnt_hi((unsigned)(mk >> 32), __builtin_amdgcn_mbcnt_lo((unsigned)mk, 0));
;                         if (sel) myidx[pos] = r * 64 + lo;
;                         base += __popcll(mk);
;                         const unsigned long long me = __ballot(uu[r] == tau);
;                         if (me != 0ull) {
;                             const int epos = ebase + __builtin_amdgcn_mbcnt_hi((unsigned)(me >> 32), __builtin_amdgcn_mbcnt_lo((unsigned)me, 0));
;                             if (uu[r] == tau && epos < 256) myidx[epos] = r * 64 + lo;
;                             ebase += __popcll(me);
;                         }
.LBB0_1087:
	s_bcnt1_i32_b64 s4, s[18:19]
	s_add_i32 s22, s24, s4
	v_cmpx_lt_u32_e64 s[18:19], s26, v96
	s_nop 1
	s_lshl_b32 s4, s22, 2
	v_mbcnt_lo_u32_b32 v99, s18, 0
	s_add_i32 s4, s96, s4
	v_mbcnt_hi_u32_b32 v99, s19, v99
	v_add_u32_e32 v98, 0x840, v97
	v_lshl_add_u32 v99, v99, 2, s4
	ds_write_b32 v99, v98
.LBB0_1089:
	s_mov_b64 exec, -1
	v_cmp_eq_u32_e32 vcc, s26, v96
	s_cbranch_vccz .LBB0_1093
	s_nop 0
	v_mbcnt_lo_u32_b32 v96, vcc_lo, 0
	v_mbcnt_hi_u32_b32 v96, vcc_hi, v96
	v_add_u32_e32 v96, s27, v96
	v_cmp_gt_i32_e64 s[20:21], s78, v96
	s_and_b64 s[4:5], vcc, s[20:21]
	s_and_saveexec_b64 s[20:21], s[4:5]
	v_add_u32_e32 v98, 0x840, v97
	v_lshl_add_u32 v96, v96, 2, s96
	ds_write_b32 v96, v98
	s_or_b64 exec, exec, s[20:21]
	s_bcnt1_i32_b64 s4, vcc
	s_add_i32 s27, s27, s4
.LBB0_1093:
	s_bcnt1_i32_b64 s4, s[18:19]
	s_add_i32 s22, s22, s4
	v_cmpx_lt_u32_e64 s[18:19], s26, v95
	s_nop 1
	s_lshl_b32 s4, s22, 2
	v_mbcnt_lo_u32_b32 v98, s18, 0
	s_add_i32 s4, s96, s4
	v_mbcnt_hi_u32_b32 v98, s19, v98
	v_add_u32_e32 v96, 0x880, v97
	v_lshl_add_u32 v98, v98, 2, s4
	ds_write_b32 v98, v96
.LBB0_1095:
	s_mov_b64 exec, -1
	v_cmp_eq_u32_e32 vcc, s26, v95
	s_cbranch_vccz .LBB0_1099
	s_nop 0
	v_mbcnt_lo_u32_b32 v95, vcc_lo, 0
	v_mbcnt_hi_u32_b32 v95, vcc_hi, v95
	v_add_u32_e32 v95, s27, v95
	v_cmp_gt_i32_e64 s[20:21], s78, v95
	s_and_b64 s[4:5], vcc, s[20:21]
	s_and_saveexec_b64 s[20:21], s[4:5]
	v_add_u32_e32 v96, 0x880, v97
	v_lshl_add_u32 v95, v95, 2, s96
	ds_write_b32 v95, v96
	s_or_b64 exec, exec, s[20:21]
	s_bcnt1_i32_b64 s4, vcc
	s_add_i32 s27, s27, s4
.LBB0_1099:
	s_bcnt1_i32_b64 s4, s[18:19]
	s_add_i32 s22, s22, s4
	v_cmpx_lt_u32_e64 s[18:19], s26, v94
	s_nop 1
	s_lshl_b32 s4, s22, 2
	v_mbcnt_lo_u32_b32 v96, s18, 0
	s_add_i32 s4, s96, s4
	v_mbcnt_hi_u32_b32 v96, s19, v96
	v_add_u32_e32 v95, 0x8c0, v97
	v_lshl_add_u32 v96, v96, 2, s4
	ds_write_b32 v96, v95
.LBB0_1101:
	s_mov_b64 exec, -1
	v_cmp_eq_u32_e32 vcc, s26, v94
	s_cbranch_vccz .LBB0_1105
	s_nop 0
	v_mbcnt_lo_u32_b32 v94, vcc_lo, 0
	v_mbcnt_hi_u32_b32 v94, vcc_hi, v94
	v_add_u32_e32 v94, s27, v94
	v_cmp_gt_i32_e64 s[20:21], s78, v94
	s_and_b64 s[4:5], vcc, s[20:21]
	s_and_saveexec_b64 s[20:21], s[4:5]
	v_add_u32_e32 v95, 0x8c0, v97
	v_lshl_add_u32 v94, v94, 2, s96
	ds_write_b32 v94, v95
	s_or_b64 exec, exec, s[20:21]
	s_bcnt1_i32_b64 s4, vcc
	s_add_i32 s27, s27, s4
.LBB0_1105:
	s_bcnt1_i32_b64 s4, s[18:19]
	s_add_i32 s22, s22, s4
	v_cmpx_lt_u32_e64 s[18:19], s26, v93
	s_nop 1
	s_lshl_b32 s4, s22, 2
	v_mbcnt_lo_u32_b32 v95, s18, 0
	s_add_i32 s4, s96, s4
	v_mbcnt_hi_u32_b32 v95, s19, v95
	v_add_u32_e32 v94, 0x900, v97
	v_lshl_add_u32 v95, v95, 2, s4
	ds_write_b32 v95, v94
.LBB0_1107:
	s_mov_b64 exec, -1
	v_cmp_eq_u32_e32 vcc, s26, v93
	s_cbranch_vccz .LBB0_1111
	s_nop 0
	v_mbcnt_lo_u32_b32 v93, vcc_lo, 0
	v_mbcnt_hi_u32_b32 v93, vcc_hi, v93
	v_add_u32_e32 v93, s27, v93
	v_cmp_gt_i32_e64 s[20:21], s78, v93
	s_and_b64 s[4:5], vcc, s[20:21]
	s_and_saveexec_b64 s[20:21], s[4:5]
	v_add_u32_e32 v94, 0x900, v97
	v_lshl_add_u32 v93, v93, 2, s96
	ds_write_b32 v93, v94
	s_or_b64 exec, exec, s[20:21]
	s_bcnt1_i32_b64 s4, vcc
	s_add_i32 s27, s27, s4
.LBB0_1111:
	s_bcnt1_i32_b64 s4, s[18:19]
	s_add_i32 s22, s22, s4
	v_cmpx_lt_u32_e64 s[18:19], s26, v92
	s_nop 1
	s_lshl_b32 s4, s22, 2
	v_mbcnt_lo_u32_b32 v94, s18, 0
	s_add_i32 s4, s96, s4
	v_mbcnt_hi_u32_b32 v94, s19, v94
	v_add_u32_e32 v93, 0x940, v97
	v_lshl_add_u32 v94, v94, 2, s4
	ds_write_b32 v94, v93
.LBB0_1113:
	s_mov_b64 exec, -1
	v_cmp_eq_u32_e32 vcc, s26, v92
	s_cbranch_vccz .LBB0_1117
	s_nop 0
	v_mbcnt_lo_u32_b32 v92, vcc_lo, 0
	v_mbcnt_hi_u32_b32 v92, vcc_hi, v92
	v_add_u32_e32 v92, s27, v92
	v_cmp_gt_i32_e64 s[20:21], s78, v92
	s_and_b64 s[4:5], vcc, s[20:21]
	s_and_saveexec_b64 s[20:21], s[4:5]
	v_add_u32_e32 v93, 0x940, v97
	v_lshl_add_u32 v92, v92, 2, s96
	ds_write_b32 v92, v93
	s_or_b64 exec, exec, s[20:21]
	s_bcnt1_i32_b64 s4, vcc
	s_add_i32 s27, s27, s4
.LBB0_1117:
	s_bcnt1_i32_b64 s4, s[18:19]
	s_add_i32 s22, s22, s4
	v_cmpx_lt_u32_e64 s[18:19], s26, v91
	s_nop 1
	s_lshl_b32 s4, s22, 2
	v_mbcnt_lo_u32_b32 v93, s18, 0
	s_add_i32 s4, s96, s4
	v_mbcnt_hi_u32_b32 v93, s19, v93
	v_add_u32_e32 v92, 0x980, v97
	v_lshl_add_u32 v93, v93, 2, s4
	ds_write_b32 v93, v92
.LBB0_1119:
	s_mov_b64 exec, -1
	v_cmp_eq_u32_e32 vcc, s26, v91
	s_cbranch_vccz .LBB0_1123
	s_nop 0
	v_mbcnt_lo_u32_b32 v91, vcc_lo, 0
	v_mbcnt_hi_u32_b32 v91, vcc_hi, v91
	v_add_u32_e32 v91, s27, v91
	v_cmp_gt_i32_e64 s[20:21], s78, v91
	s_and_b64 s[4:5], vcc, s[20:21]
	s_and_saveexec_b64 s[20:21], s[4:5]
	v_add_u32_e32 v92, 0x980, v97
	v_lshl_add_u32 v91, v91, 2, s96
	ds_write_b32 v91, v92
	s_or_b64 exec, exec, s[20:21]
	s_bcnt1_i32_b64 s4, vcc
	s_add_i32 s27, s27, s4
.LBB0_1123:
	s_bcnt1_i32_b64 s4, s[18:19]
	s_add_i32 s22, s22, s4
	v_cmpx_lt_u32_e64 s[18:19], s26, v90
	s_nop 1
	s_lshl_b32 s4, s22, 2
	v_mbcnt_lo_u32_b32 v92, s18, 0
	s_add_i32 s4, s96, s4
	v_mbcnt_hi_u32_b32 v92, s19, v92
	v_add_u32_e32 v91, 0x9c0, v97
	v_lshl_add_u32 v92, v92, 2, s4
	ds_write_b32 v92, v91
.LBB0_1125:
	s_mov_b64 exec, -1
	v_cmp_eq_u32_e32 vcc, s26, v90
	s_cbranch_vccz .LBB0_1129
	s_nop 0
	v_mbcnt_lo_u32_b32 v90, vcc_lo, 0
	v_mbcnt_hi_u32_b32 v90, vcc_hi, v90
	v_add_u32_e32 v90, s27, v90
	v_cmp_gt_i32_e64 s[20:21], s78, v90
	s_and_b64 s[4:5], vcc, s[20:21]
	s_and_saveexec_b64 s[20:21], s[4:5]
	v_add_u32_e32 v91, 0x9c0, v97
	v_lshl_add_u32 v90, v90, 2, s96
	ds_write_b32 v90, v91
	s_or_b64 exec, exec, s[20:21]
	s_bcnt1_i32_b64 s4, vcc
	s_add_i32 s27, s27, s4
; __device__ __forceinline__ void dsa_tile(const Params& p, unsigned char* smem, int tile) {
;     ...
;                     for (int r = g * 16; r < g * 16 + 16; ++r) {
;                         const bool sel = uu[r] > tau;
;                         const unsigned long long mk = __ballot(sel);
;                         const int pos = base + __builtin_amdgcn_mbcnt_hi((unsigned)(mk >> 32), __builtin_amdgcn_mbcnt_lo((unsigned)mk, 0));
;                         if (sel) myidx[pos] = r * 64 + lo;
;                         base += __popcll(mk);
;                         const unsigned long long me = __ballot(uu[r] == tau);
;                         if (me != 0ull) {
;                             const int epos = ebase + __builtin_amdgcn_mbcnt_hi((unsigned)(me >> 32), __builtin_amdgcn_mbcnt_lo((unsigned)me, 0));
;                             if (uu[r] == tau && epos < 256) myidx[epos] = r * 64 + lo;
;                             ebase += __popcll(me);
;                         }
.LBB0_1129:
	s_bcnt1_i32_b64 s4, s[18:19]
	s_add_i32 s22, s22, s4
	v_cmpx_lt_u32_e64 s[18:19], s26, v89
	s_nop 1
	s_lshl_b32 s4, s22, 2
	v_mbcnt_lo_u32_b32 v91, s18, 0
	s_add_i32 s4, s96, s4
	v_mbcnt_hi_u32_b32 v91, s19, v91
	v_add_u32_e32 v90, 0xa00, v97
	v_lshl_add_u32 v91, v91, 2, s4
	ds_write_b32 v91, v90
.LBB0_1131:
	s_mov_b64 exec, -1
	v_cmp_eq_u32_e32 vcc, s26, v89
	s_cbranch_vccz .LBB0_1135
	s_nop 0
	v_mbcnt_lo_u32_b32 v89, vcc_lo, 0
	v_mbcnt_hi_u32_b32 v89, vcc_hi, v89
	v_add_u32_e32 v89, s27, v89
	v_cmp_gt_i32_e64 s[20:21], s78, v89
	s_and_b64 s[4:5], vcc, s[20:21]
	s_and_saveexec_b64 s[20:21], s[4:5]
	v_add_u32_e32 v90, 0xa00, v97
	v_lshl_add_u32 v89, v89, 2, s96
	ds_write_b32 v89, v90
	s_or_b64 exec, exec, s[20:21]
	s_bcnt1_i32_b64 s4, vcc
	s_add_i32 s27, s27, s4
.LBB0_1135:
	s_bcnt1_i32_b64 s4, s[18:19]
	s_add_i32 s22, s22, s4
	v_cmpx_lt_u32_e64 s[18:19], s26, v88
	s_nop 1
	s_lshl_b32 s4, s22, 2
	v_mbcnt_lo_u32_b32 v90, s18, 0
	s_add_i32 s4, s96, s4
	v_mbcnt_hi_u32_b32 v90, s19, v90
	v_add_u32_e32 v89, 0xa40, v97
	v_lshl_add_u32 v90, v90, 2, s4
	ds_write_b32 v90, v89
.LBB0_1137:
	s_mov_b64 exec, -1
	v_cmp_eq_u32_e32 vcc, s26, v88
	s_cbranch_vccz .LBB0_1141
	s_nop 0
	v_mbcnt_lo_u32_b32 v88, vcc_lo, 0
	v_mbcnt_hi_u32_b32 v88, vcc_hi, v88
	v_add_u32_e32 v88, s27, v88
	v_cmp_gt_i32_e64 s[20:21], s78, v88
	s_and_b64 s[4:5], vcc, s[20:21]
	s_and_saveexec_b64 s[20:21], s[4:5]
	v_add_u32_e32 v89, 0xa40, v97
	v_lshl_add_u32 v88, v88, 2, s96
	ds_write_b32 v88, v89
	s_or_b64 exec, exec, s[20:21]
	s_bcnt1_i32_b64 s4, vcc
	s_add_i32 s27, s27, s4
.LBB0_1141:
	s_bcnt1_i32_b64 s4, s[18:19]
	s_add_i32 s22, s22, s4
	v_cmpx_lt_u32_e64 s[18:19], s26, v87
	s_nop 1
	s_lshl_b32 s4, s22, 2
	v_mbcnt_lo_u32_b32 v89, s18, 0
	s_add_i32 s4, s96, s4
	v_mbcnt_hi_u32_b32 v89, s19, v89
	v_add_u32_e32 v88, 0xa80, v97
	v_lshl_add_u32 v89, v89, 2, s4
	ds_write_b32 v89, v88
.LBB0_1143:
	s_mov_b64 exec, -1
	v_cmp_eq_u32_e32 vcc, s26, v87
	s_cbranch_vccz .LBB0_1147
	s_nop 0
	v_mbcnt_lo_u32_b32 v87, vcc_lo, 0
	v_mbcnt_hi_u32_b32 v87, vcc_hi, v87
	v_add_u32_e32 v87, s27, v87
	v_cmp_gt_i32_e64 s[20:21], s78, v87
	s_and_b64 s[4:5], vcc, s[20:21]
	s_and_saveexec_b64 s[20:21], s[4:5]
	v_add_u32_e32 v88, 0xa80, v97
	v_lshl_add_u32 v87, v87, 2, s96
	ds_write_b32 v87, v88
	s_or_b64 exec, exec, s[20:21]
	s_bcnt1_i32_b64 s4, vcc
	s_add_i32 s27, s27, s4
.LBB0_1147:
	s_bcnt1_i32_b64 s4, s[18:19]
	s_add_i32 s22, s22, s4
	v_cmpx_lt_u32_e64 s[18:19], s26, v86
	s_nop 1
	s_lshl_b32 s4, s22, 2
	v_mbcnt_lo_u32_b32 v88, s18, 0
	s_add_i32 s4, s96, s4
	v_mbcnt_hi_u32_b32 v88, s19, v88
	v_add_u32_e32 v87, 0xac0, v97
	v_lshl_add_u32 v88, v88, 2, s4
	ds_write_b32 v88, v87
.LBB0_1149:
	s_mov_b64 exec, -1
	v_cmp_eq_u32_e32 vcc, s26, v86
	s_cbranch_vccz .LBB0_1153
	s_nop 0
	v_mbcnt_lo_u32_b32 v86, vcc_lo, 0
	v_mbcnt_hi_u32_b32 v86, vcc_hi, v86
	v_add_u32_e32 v86, s27, v86
	v_cmp_gt_i32_e64 s[20:21], s78, v86
	s_and_b64 s[4:5], vcc, s[20:21]
	s_and_saveexec_b64 s[20:21], s[4:5]
	v_add_u32_e32 v87, 0xac0, v97
	v_lshl_add_u32 v86, v86, 2, s96
	ds_write_b32 v86, v87
	s_or_b64 exec, exec, s[20:21]
	s_bcnt1_i32_b64 s4, vcc
	s_add_i32 s27, s27, s4
.LBB0_1153:
	s_bcnt1_i32_b64 s4, s[18:19]
	s_add_i32 s22, s22, s4
	v_cmpx_lt_u32_e64 s[18:19], s26, v85
	s_nop 1
	s_lshl_b32 s4, s22, 2
	v_mbcnt_lo_u32_b32 v87, s18, 0
	s_add_i32 s4, s96, s4
	v_mbcnt_hi_u32_b32 v87, s19, v87
	v_add_u32_e32 v86, 0xb00, v97
	v_lshl_add_u32 v87, v87, 2, s4
	ds_write_b32 v87, v86
.LBB0_1155:
	s_mov_b64 exec, -1
	v_cmp_eq_u32_e32 vcc, s26, v85
	s_cbranch_vccz .LBB0_1159
	s_nop 0
	v_mbcnt_lo_u32_b32 v85, vcc_lo, 0
	v_mbcnt_hi_u32_b32 v85, vcc_hi, v85
	v_add_u32_e32 v85, s27, v85
	v_cmp_gt_i32_e64 s[20:21], s78, v85
	s_and_b64 s[4:5], vcc, s[20:21]
	s_and_saveexec_b64 s[20:21], s[4:5]
	v_add_u32_e32 v86, 0xb00, v97
	v_lshl_add_u32 v85, v85, 2, s96
	ds_write_b32 v85, v86
	s_or_b64 exec, exec, s[20:21]
	s_bcnt1_i32_b64 s4, vcc
	s_add_i32 s27, s27, s4
.LBB0_1159:
	s_bcnt1_i32_b64 s4, s[18:19]
	s_add_i32 s22, s22, s4
	v_cmpx_lt_u32_e64 s[18:19], s26, v84
	s_nop 1
	s_lshl_b32 s4, s22, 2
	v_mbcnt_lo_u32_b32 v86, s18, 0
	s_add_i32 s4, s96, s4
	v_mbcnt_hi_u32_b32 v86, s19, v86
	v_add_u32_e32 v85, 0xb40, v97
	v_lshl_add_u32 v86, v86, 2, s4
	ds_write_b32 v86, v85
.LBB0_1161:
	s_mov_b64 exec, -1
	v_cmp_eq_u32_e32 vcc, s26, v84
	s_cbranch_vccz .LBB0_1165
	s_nop 0
	v_mbcnt_lo_u32_b32 v84, vcc_lo, 0
	v_mbcnt_hi_u32_b32 v84, vcc_hi, v84
	v_add_u32_e32 v84, s27, v84
	v_cmp_gt_i32_e64 s[20:21], s78, v84
	s_and_b64 s[4:5], vcc, s[20:21]
	s_and_saveexec_b64 s[20:21], s[4:5]
	v_add_u32_e32 v85, 0xb40, v97
	v_lshl_add_u32 v84, v84, 2, s96
	ds_write_b32 v84, v85
	s_or_b64 exec, exec, s[20:21]
	s_bcnt1_i32_b64 s4, vcc
	s_add_i32 s27, s27, s4
.LBB0_1165:
	s_bcnt1_i32_b64 s4, s[18:19]
	s_add_i32 s22, s22, s4
	v_cmpx_lt_u32_e64 s[18:19], s26, v83
	s_nop 1
	s_lshl_b32 s4, s22, 2
	v_mbcnt_lo_u32_b32 v85, s18, 0
	s_add_i32 s4, s96, s4
	v_mbcnt_hi_u32_b32 v85, s19, v85
	v_add_u32_e32 v84, 0xb80, v97
	v_lshl_add_u32 v85, v85, 2, s4
	ds_write_b32 v85, v84
.LBB0_1167:
	s_mov_b64 exec, -1
	v_cmp_eq_u32_e32 vcc, s26, v83
	s_cbranch_vccz .LBB0_1171
	s_nop 0
	v_mbcnt_lo_u32_b32 v83, vcc_lo, 0
	v_mbcnt_hi_u32_b32 v83, vcc_hi, v83
	v_add_u32_e32 v83, s27, v83
	v_cmp_gt_i32_e64 s[20:21], s78, v83
	s_and_b64 s[4:5], vcc, s[20:21]
	s_and_saveexec_b64 s[20:21], s[4:5]
	v_add_u32_e32 v84, 0xb80, v97
	v_lshl_add_u32 v83, v83, 2, s96
	ds_write_b32 v83, v84
	s_or_b64 exec, exec, s[20:21]
	s_bcnt1_i32_b64 s4, vcc
	s_add_i32 s27, s27, s4
.LBB0_1171:
	s_bcnt1_i32_b64 s4, s[18:19]
	s_add_i32 s22, s22, s4
	v_cmpx_lt_u32_e64 s[18:19], s26, v79
	s_nop 1
	s_lshl_b32 s4, s22, 2
	v_mbcnt_lo_u32_b32 v84, s18, 0
	s_add_i32 s4, s96, s4
	v_mbcnt_hi_u32_b32 v84, s19, v84
	v_add_u32_e32 v83, 0xbc0, v97
	v_lshl_add_u32 v84, v84, 2, s4
	ds_write_b32 v84, v83
.LBB0_1173:
	s_mov_b64 exec, -1
	v_cmp_eq_u32_e32 vcc, s26, v79
	s_cbranch_vccz .LBB0_1177
	s_nop 0
	v_mbcnt_lo_u32_b32 v79, vcc_lo, 0
	v_mbcnt_hi_u32_b32 v79, vcc_hi, v79
	v_add_u32_e32 v79, s27, v79
	v_cmp_gt_i32_e64 s[20:21], s78, v79
	s_and_b64 s[4:5], vcc, s[20:21]
	s_and_saveexec_b64 s[20:21], s[4:5]
	v_add_u32_e32 v83, 0xbc0, v97
	v_lshl_add_u32 v79, v79, 2, s96
	ds_write_b32 v79, v83
	s_or_b64 exec, exec, s[20:21]
	s_bcnt1_i32_b64 s4, vcc
	s_add_i32 s27, s27, s4

; __device__ __forceinline__ void dsa_tile(const Params& p, unsigned char* smem, int tile) {
;     ...
;                     for (int r = g * 16; r < g * 16 + 16; ++r) {
;                         const bool sel = uu[r] > tau;
;                         const unsigned long long mk = __ballot(sel);
;                         const int pos = base + __builtin_amdgcn_mbcnt_hi((unsigned)(mk >> 32), __builtin_amdgcn_mbcnt_lo((unsigned)mk, 0));
;                         if (sel) myidx[pos] = r * 64 + lo;
;                         base += __popcll(mk);
;                         const unsigned long long me = __ballot(uu[r] == tau);
;                         if (me != 0ull) {
;                             const int epos = ebase + __builtin_amdgcn_mbcnt_hi((unsigned)(me >> 32), __builtin_amdgcn_mbcnt_lo((unsigned)me, 0));
;                             if (uu[r] == tau && epos < 256) myidx[epos] = r * 64 + lo;
;                             ebase += __popcll(me);
;                         }
.LBB0_1184:
	s_bcnt1_i32_b64 s4, s[16:17]
	s_add_i32 s20, s24, s4
	v_cmpx_lt_u32_e64 s[16:17], s26, v81
	s_nop 1
	s_lshl_b32 s4, s20, 2
	v_mbcnt_lo_u32_b32 v83, s16, 0
	s_add_i32 s4, s96, s4
	v_mbcnt_hi_u32_b32 v83, s17, v83
	v_add_u32_e32 v82, 0xc40, v79
	v_lshl_add_u32 v83, v83, 2, s4
	ds_write_b32 v83, v82
.LBB0_1186:
	s_mov_b64 exec, -1
	v_cmp_eq_u32_e32 vcc, s26, v81
	s_cbranch_vccz .LBB0_1190
	s_nop 0
	v_mbcnt_lo_u32_b32 v81, vcc_lo, 0
	v_mbcnt_hi_u32_b32 v81, vcc_hi, v81
	v_add_u32_e32 v81, s27, v81
	v_cmp_gt_i32_e64 s[18:19], s78, v81
	s_and_b64 s[4:5], vcc, s[18:19]
	s_and_saveexec_b64 s[18:19], s[4:5]
	v_add_u32_e32 v82, 0xc40, v79
	v_lshl_add_u32 v81, v81, 2, s96
	ds_write_b32 v81, v82
	s_or_b64 exec, exec, s[18:19]
	s_bcnt1_i32_b64 s4, vcc
	s_add_i32 s27, s27, s4
.LBB0_1190:
	s_bcnt1_i32_b64 s4, s[16:17]
	s_add_i32 s20, s20, s4
	v_cmpx_lt_u32_e64 s[16:17], s26, v80
	s_nop 1
	s_lshl_b32 s4, s20, 2
	v_mbcnt_lo_u32_b32 v82, s16, 0
	s_add_i32 s4, s96, s4
	v_mbcnt_hi_u32_b32 v82, s17, v82
	v_add_u32_e32 v81, 0xc80, v79
	v_lshl_add_u32 v82, v82, 2, s4
	ds_write_b32 v82, v81
.LBB0_1192:
	s_mov_b64 exec, -1
	v_cmp_eq_u32_e32 vcc, s26, v80
	s_cbranch_vccz .LBB0_1196
	s_nop 0
	v_mbcnt_lo_u32_b32 v80, vcc_lo, 0
	v_mbcnt_hi_u32_b32 v80, vcc_hi, v80
	v_add_u32_e32 v80, s27, v80
	v_cmp_gt_i32_e64 s[18:19], s78, v80
	s_and_b64 s[4:5], vcc, s[18:19]
	s_and_saveexec_b64 s[18:19], s[4:5]
	v_add_u32_e32 v81, 0xc80, v79
	v_lshl_add_u32 v80, v80, 2, s96
	ds_write_b32 v80, v81
	s_or_b64 exec, exec, s[18:19]
	s_bcnt1_i32_b64 s4, vcc
	s_add_i32 s27, s27, s4
.LBB0_1196:
	s_bcnt1_i32_b64 s4, s[16:17]
	s_add_i32 s20, s20, s4
	v_cmpx_lt_u32_e64 s[16:17], s26, v78
	s_nop 1
	s_lshl_b32 s4, s20, 2
	v_mbcnt_lo_u32_b32 v81, s16, 0
	s_add_i32 s4, s96, s4
	v_mbcnt_hi_u32_b32 v81, s17, v81
	v_add_u32_e32 v80, 0xcc0, v79
	v_lshl_add_u32 v81, v81, 2, s4
	ds_write_b32 v81, v80
.LBB0_1198:
	s_mov_b64 exec, -1
	v_cmp_eq_u32_e32 vcc, s26, v78
	s_cbranch_vccz .LBB0_1202
	s_nop 0
	v_mbcnt_lo_u32_b32 v78, vcc_lo, 0
	v_mbcnt_hi_u32_b32 v78, vcc_hi, v78
	v_add_u32_e32 v78, s27, v78
	v_cmp_gt_i32_e64 s[18:19], s78, v78
	s_and_b64 s[4:5], vcc, s[18:19]
	s_and_saveexec_b64 s[18:19], s[4:5]
	v_add_u32_e32 v80, 0xcc0, v79
	v_lshl_add_u32 v78, v78, 2, s96
	ds_write_b32 v78, v80
	s_or_b64 exec, exec, s[18:19]
	s_bcnt1_i32_b64 s4, vcc
	s_add_i32 s27, s27, s4
.LBB0_1202:
	s_bcnt1_i32_b64 s4, s[16:17]
	s_add_i32 s20, s20, s4
	v_cmpx_lt_u32_e64 s[16:17], s26, v77
	s_nop 1
	s_lshl_b32 s4, s20, 2
	v_mbcnt_lo_u32_b32 v80, s16, 0
	s_add_i32 s4, s96, s4
	v_mbcnt_hi_u32_b32 v80, s17, v80
	v_add_u32_e32 v78, 0xd00, v79
	v_lshl_add_u32 v80, v80, 2, s4
	ds_write_b32 v80, v78
.LBB0_1204:
	s_mov_b64 exec, -1
	v_cmp_eq_u32_e32 vcc, s26, v77
	s_cbranch_vccz .LBB0_1208
	s_nop 0
	v_mbcnt_lo_u32_b32 v77, vcc_lo, 0
	v_mbcnt_hi_u32_b32 v77, vcc_hi, v77
	v_add_u32_e32 v77, s27, v77
	v_cmp_gt_i32_e64 s[18:19], s78, v77
	s_and_b64 s[4:5], vcc, s[18:19]
	s_and_saveexec_b64 s[18:19], s[4:5]
	v_add_u32_e32 v78, 0xd00, v79
	v_lshl_add_u32 v77, v77, 2, s96
	ds_write_b32 v77, v78
	s_or_b64 exec, exec, s[18:19]
	s_bcnt1_i32_b64 s4, vcc
	s_add_i32 s27, s27, s4
.LBB0_1208:
	s_bcnt1_i32_b64 s4, s[16:17]
	s_add_i32 s20, s20, s4
	v_cmpx_lt_u32_e64 s[16:17], s26, v76
	s_nop 1
	s_lshl_b32 s4, s20, 2
	v_mbcnt_lo_u32_b32 v78, s16, 0
	s_add_i32 s4, s96, s4
	v_mbcnt_hi_u32_b32 v78, s17, v78
	v_add_u32_e32 v77, 0xd40, v79
	v_lshl_add_u32 v78, v78, 2, s4
	ds_write_b32 v78, v77
.LBB0_1210:
	s_mov_b64 exec, -1
	v_cmp_eq_u32_e32 vcc, s26, v76
	s_cbranch_vccz .LBB0_1214
	s_nop 0
	v_mbcnt_lo_u32_b32 v76, vcc_lo, 0
	v_mbcnt_hi_u32_b32 v76, vcc_hi, v76
	v_add_u32_e32 v76, s27, v76
	v_cmp_gt_i32_e64 s[18:19], s78, v76
	s_and_b64 s[4:5], vcc, s[18:19]
	s_and_saveexec_b64 s[18:19], s[4:5]
	v_add_u32_e32 v77, 0xd40, v79
	v_lshl_add_u32 v76, v76, 2, s96
	ds_write_b32 v76, v77
	s_or_b64 exec, exec, s[18:19]
	s_bcnt1_i32_b64 s4, vcc
	s_add_i32 s27, s27, s4
.LBB0_1214:
	s_bcnt1_i32_b64 s4, s[16:17]
	s_add_i32 s20, s20, s4
	v_cmpx_lt_u32_e64 s[16:17], s26, v75
	s_nop 1
	s_lshl_b32 s4, s20, 2
	v_mbcnt_lo_u32_b32 v77, s16, 0
	s_add_i32 s4, s96, s4
	v_mbcnt_hi_u32_b32 v77, s17, v77
	v_add_u32_e32 v76, 0xd80, v79
	v_lshl_add_u32 v77, v77, 2, s4
	ds_write_b32 v77, v76
.LBB0_1216:
	s_mov_b64 exec, -1
	v_cmp_eq_u32_e32 vcc, s26, v75
	s_cbranch_vccz .LBB0_1220
	s_nop 0
	v_mbcnt_lo_u32_b32 v75, vcc_lo, 0
	v_mbcnt_hi_u32_b32 v75, vcc_hi, v75
	v_add_u32_e32 v75, s27, v75
	v_cmp_gt_i32_e64 s[18:19], s78, v75
	s_and_b64 s[4:5], vcc, s[18:19]
	s_and_saveexec_b64 s[18:19], s[4:5]
	v_add_u32_e32 v76, 0xd80, v79
	v_lshl_add_u32 v75, v75, 2, s96
	ds_write_b32 v75, v76
	s_or_b64 exec, exec, s[18:19]
	s_bcnt1_i32_b64 s4, vcc
	s_add_i32 s27, s27, s4
.LBB0_1220:
	s_bcnt1_i32_b64 s4, s[16:17]
	s_add_i32 s20, s20, s4
	v_cmpx_lt_u32_e64 s[16:17], s26, v74
	s_nop 1
	s_lshl_b32 s4, s20, 2
	v_mbcnt_lo_u32_b32 v76, s16, 0
	s_add_i32 s4, s96, s4
	v_mbcnt_hi_u32_b32 v76, s17, v76
	v_add_u32_e32 v75, 0xdc0, v79
	v_lshl_add_u32 v76, v76, 2, s4
	ds_write_b32 v76, v75
.LBB0_1222:
	s_mov_b64 exec, -1
	v_cmp_eq_u32_e32 vcc, s26, v74
	s_cbranch_vccz .LBB0_1226
	s_nop 0
	v_mbcnt_lo_u32_b32 v74, vcc_lo, 0
	v_mbcnt_hi_u32_b32 v74, vcc_hi, v74
	v_add_u32_e32 v74, s27, v74
	v_cmp_gt_i32_e64 s[18:19], s78, v74
	s_and_b64 s[4:5], vcc, s[18:19]
	s_and_saveexec_b64 s[18:19], s[4:5]
	v_add_u32_e32 v75, 0xdc0, v79
	v_lshl_add_u32 v74, v74, 2, s96
	ds_write_b32 v74, v75
	s_or_b64 exec, exec, s[18:19]
	s_bcnt1_i32_b64 s4, vcc
	s_add_i32 s27, s27, s4
; __device__ __forceinline__ void dsa_tile(const Params& p, unsigned char* smem, int tile) {
;     ...
;                     for (int r = g * 16; r < g * 16 + 16; ++r) {
;                         const bool sel = uu[r] > tau;
;                         const unsigned long long mk = __ballot(sel);
;                         const int pos = base + __builtin_amdgcn_mbcnt_hi((unsigned)(mk >> 32), __builtin_amdgcn_mbcnt_lo((unsigned)mk, 0));
;                         if (sel) myidx[pos] = r * 64 + lo;
;                         base += __popcll(mk);
;                         const unsigned long long me = __ballot(uu[r] == tau);
;                         if (me != 0ull) {
;                             const int epos = ebase + __builtin_amdgcn_mbcnt_hi((unsigned)(me >> 32), __builtin_amdgcn_mbcnt_lo((unsigned)me, 0));
;                             if (uu[r] == tau && epos < 256) myidx[epos] = r * 64 + lo;
;                             ebase += __popcll(me);
;                         }
.LBB0_1226:
	s_bcnt1_i32_b64 s4, s[16:17]
	s_add_i32 s20, s20, s4
	v_cmpx_lt_u32_e64 s[16:17], s26, v73
	s_nop 1
	s_lshl_b32 s4, s20, 2
	v_mbcnt_lo_u32_b32 v75, s16, 0
	s_add_i32 s4, s96, s4
	v_mbcnt_hi_u32_b32 v75, s17, v75
	v_add_u32_e32 v74, 0xe00, v79
	v_lshl_add_u32 v75, v75, 2, s4
	ds_write_b32 v75, v74
.LBB0_1228:
	s_mov_b64 exec, -1
	v_cmp_eq_u32_e32 vcc, s26, v73
	s_cbranch_vccz .LBB0_1232
	s_nop 0
	v_mbcnt_lo_u32_b32 v73, vcc_lo, 0
	v_mbcnt_hi_u32_b32 v73, vcc_hi, v73
	v_add_u32_e32 v73, s27, v73
	v_cmp_gt_i32_e64 s[18:19], s78, v73
	s_and_b64 s[4:5], vcc, s[18:19]
	s_and_saveexec_b64 s[18:19], s[4:5]
	v_add_u32_e32 v74, 0xe00, v79
	v_lshl_add_u32 v73, v73, 2, s96
	ds_write_b32 v73, v74
	s_or_b64 exec, exec, s[18:19]
	s_bcnt1_i32_b64 s4, vcc
	s_add_i32 s27, s27, s4
.LBB0_1232:
	s_bcnt1_i32_b64 s4, s[16:17]
	s_add_i32 s20, s20, s4
	v_cmpx_lt_u32_e64 s[16:17], s26, v72
	s_nop 1
	s_lshl_b32 s4, s20, 2
	v_mbcnt_lo_u32_b32 v74, s16, 0
	s_add_i32 s4, s96, s4
	v_mbcnt_hi_u32_b32 v74, s17, v74
	v_add_u32_e32 v73, 0xe40, v79
	v_lshl_add_u32 v74, v74, 2, s4
	ds_write_b32 v74, v73
.LBB0_1234:
	s_mov_b64 exec, -1
	v_cmp_eq_u32_e32 vcc, s26, v72
	s_cbranch_vccz .LBB0_1238
	s_nop 0
	v_mbcnt_lo_u32_b32 v72, vcc_lo, 0
	v_mbcnt_hi_u32_b32 v72, vcc_hi, v72
	v_add_u32_e32 v72, s27, v72
	v_cmp_gt_i32_e64 s[18:19], s78, v72
	s_and_b64 s[4:5], vcc, s[18:19]
	s_and_saveexec_b64 s[18:19], s[4:5]
	v_add_u32_e32 v73, 0xe40, v79
	v_lshl_add_u32 v72, v72, 2, s96
	ds_write_b32 v72, v73
	s_or_b64 exec, exec, s[18:19]
	s_bcnt1_i32_b64 s4, vcc
	s_add_i32 s27, s27, s4
.LBB0_1238:
	s_bcnt1_i32_b64 s4, s[16:17]
	s_add_i32 s20, s20, s4
	v_cmpx_lt_u32_e64 s[16:17], s26, v71
	s_nop 1
	s_lshl_b32 s4, s20, 2
	v_mbcnt_lo_u32_b32 v73, s16, 0
	s_add_i32 s4, s96, s4
	v_mbcnt_hi_u32_b32 v73, s17, v73
	v_add_u32_e32 v72, 0xe80, v79
	v_lshl_add_u32 v73, v73, 2, s4
	ds_write_b32 v73, v72
.LBB0_1240:
	s_mov_b64 exec, -1
	v_cmp_eq_u32_e32 vcc, s26, v71
	s_cbranch_vccz .LBB0_1244
	s_nop 0
	v_mbcnt_lo_u32_b32 v71, vcc_lo, 0
	v_mbcnt_hi_u32_b32 v71, vcc_hi, v71
	v_add_u32_e32 v71, s27, v71
	v_cmp_gt_i32_e64 s[18:19], s78, v71
	s_and_b64 s[4:5], vcc, s[18:19]
	s_and_saveexec_b64 s[18:19], s[4:5]
	v_add_u32_e32 v72, 0xe80, v79
	v_lshl_add_u32 v71, v71, 2, s96
	ds_write_b32 v71, v72
	s_or_b64 exec, exec, s[18:19]
	s_bcnt1_i32_b64 s4, vcc
	s_add_i32 s27, s27, s4
.LBB0_1244:
	s_bcnt1_i32_b64 s4, s[16:17]
	s_add_i32 s20, s20, s4
	v_cmpx_lt_u32_e64 s[16:17], s26, v70
	s_nop 1
	s_lshl_b32 s4, s20, 2
	v_mbcnt_lo_u32_b32 v72, s16, 0
	s_add_i32 s4, s96, s4
	v_mbcnt_hi_u32_b32 v72, s17, v72
	v_add_u32_e32 v71, 0xec0, v79
	v_lshl_add_u32 v72, v72, 2, s4
	ds_write_b32 v72, v71
.LBB0_1246:
	s_mov_b64 exec, -1
	v_cmp_eq_u32_e32 vcc, s26, v70
	s_cbranch_vccz .LBB0_1250
	s_nop 0
	v_mbcnt_lo_u32_b32 v70, vcc_lo, 0
	v_mbcnt_hi_u32_b32 v70, vcc_hi, v70
	v_add_u32_e32 v70, s27, v70
	v_cmp_gt_i32_e64 s[18:19], s78, v70
	s_and_b64 s[4:5], vcc, s[18:19]
	s_and_saveexec_b64 s[18:19], s[4:5]
	v_add_u32_e32 v71, 0xec0, v79
	v_lshl_add_u32 v70, v70, 2, s96
	ds_write_b32 v70, v71
	s_or_b64 exec, exec, s[18:19]
	s_bcnt1_i32_b64 s4, vcc
	s_add_i32 s27, s27, s4
.LBB0_1250:
	s_bcnt1_i32_b64 s4, s[16:17]
	s_add_i32 s20, s20, s4
	v_cmpx_lt_u32_e64 s[16:17], s26, v69
	s_nop 1
	s_lshl_b32 s4, s20, 2
	v_mbcnt_lo_u32_b32 v71, s16, 0
	s_add_i32 s4, s96, s4
	v_mbcnt_hi_u32_b32 v71, s17, v71
	v_add_u32_e32 v70, 0xf00, v79
	v_lshl_add_u32 v71, v71, 2, s4
	ds_write_b32 v71, v70
.LBB0_1252:
	s_mov_b64 exec, -1
	v_cmp_eq_u32_e32 vcc, s26, v69
	s_cbranch_vccz .LBB0_1256
	s_nop 0
	v_mbcnt_lo_u32_b32 v69, vcc_lo, 0
	v_mbcnt_hi_u32_b32 v69, vcc_hi, v69
	v_add_u32_e32 v69, s27, v69
	v_cmp_gt_i32_e64 s[18:19], s78, v69
	s_and_b64 s[4:5], vcc, s[18:19]
	s_and_saveexec_b64 s[18:19], s[4:5]
	v_add_u32_e32 v70, 0xf00, v79
	v_lshl_add_u32 v69, v69, 2, s96
	ds_write_b32 v69, v70
	s_or_b64 exec, exec, s[18:19]
	s_bcnt1_i32_b64 s4, vcc
	s_add_i32 s27, s27, s4
.LBB0_1256:
	s_bcnt1_i32_b64 s4, s[16:17]
	s_add_i32 s20, s20, s4
	v_cmpx_lt_u32_e64 s[16:17], s26, v68
	s_nop 1
	s_lshl_b32 s4, s20, 2
	v_mbcnt_lo_u32_b32 v70, s16, 0
	s_add_i32 s4, s96, s4
	v_mbcnt_hi_u32_b32 v70, s17, v70
	v_add_u32_e32 v69, 0xf40, v79
	v_lshl_add_u32 v70, v70, 2, s4
	ds_write_b32 v70, v69
.LBB0_1258:
	s_mov_b64 exec, -1
	v_cmp_eq_u32_e32 vcc, s26, v68
	s_cbranch_vccz .LBB0_1262
	s_nop 0
	v_mbcnt_lo_u32_b32 v68, vcc_lo, 0
	v_mbcnt_hi_u32_b32 v68, vcc_hi, v68
	v_add_u32_e32 v68, s27, v68
	v_cmp_gt_i32_e64 s[18:19], s78, v68
	s_and_b64 s[4:5], vcc, s[18:19]
	s_and_saveexec_b64 s[18:19], s[4:5]
	v_add_u32_e32 v69, 0xf40, v79
	v_lshl_add_u32 v68, v68, 2, s96
	ds_write_b32 v68, v69
	s_or_b64 exec, exec, s[18:19]
	s_bcnt1_i32_b64 s4, vcc
	s_add_i32 s27, s27, s4
.LBB0_1262:
	s_bcnt1_i32_b64 s4, s[16:17]
	s_add_i32 s20, s20, s4
	v_cmpx_lt_u32_e64 s[16:17], s26, v67
	s_nop 1
	s_lshl_b32 s4, s20, 2
	v_mbcnt_lo_u32_b32 v69, s16, 0
	s_add_i32 s4, s96, s4
	v_mbcnt_hi_u32_b32 v69, s17, v69
	v_add_u32_e32 v68, 0xf80, v79
	v_lshl_add_u32 v69, v69, 2, s4
	ds_write_b32 v69, v68
.LBB0_1264:
	s_mov_b64 exec, -1
	v_cmp_eq_u32_e32 vcc, s26, v67
	s_cbranch_vccz .LBB0_1268
	s_nop 0
	v_mbcnt_lo_u32_b32 v67, vcc_lo, 0
	v_mbcnt_hi_u32_b32 v67, vcc_hi, v67
	v_add_u32_e32 v67, s27, v67
	v_cmp_gt_i32_e64 s[18:19], s78, v67
	s_and_b64 s[4:5], vcc, s[18:19]
	s_and_saveexec_b64 s[18:19], s[4:5]
	v_add_u32_e32 v68, 0xf80, v79
	v_lshl_add_u32 v67, v67, 2, s96
	ds_write_b32 v67, v68
	s_or_b64 exec, exec, s[18:19]
	s_bcnt1_i32_b64 s4, vcc
	s_add_i32 s27, s27, s4
.LBB0_1268:
	s_bcnt1_i32_b64 s4, s[16:17]
	s_add_i32 s20, s20, s4
	v_cmpx_lt_u32_e64 s[16:17], s26, v65
	s_nop 1
	s_lshl_b32 s4, s20, 2
	v_mbcnt_lo_u32_b32 v68, s16, 0
	s_add_i32 s4, s96, s4
	v_mbcnt_hi_u32_b32 v68, s17, v68
	v_add_u32_e32 v67, 0xfc0, v79
	v_lshl_add_u32 v68, v68, 2, s4
	ds_write_b32 v68, v67
.LBB0_1270:
	s_mov_b64 exec, -1
	v_cmp_eq_u32_e32 vcc, s26, v65
	s_cbranch_vccz .LBB0_1274
	s_nop 0
	v_mbcnt_lo_u32_b32 v65, vcc_lo, 0
	v_mbcnt_hi_u32_b32 v65, vcc_hi, v65
	v_add_u32_e32 v65, s27, v65
	v_cmp_gt_i32_e64 s[18:19], s78, v65
	s_and_b64 s[4:5], vcc, s[18:19]
	s_and_saveexec_b64 s[18:19], s[4:5]
	v_add_u32_e32 v67, 0xfc0, v79
	v_lshl_add_u32 v65, v65, 2, s96
	ds_write_b32 v65, v67
	s_or_b64 exec, exec, s[18:19]
	s_bcnt1_i32_b64 s4, vcc
	s_add_i32 s27, s27, s4

; __device__ __forceinline__ void dsa_tile(const Params& p, unsigned char* smem, int tile) {
;     ...
;                     for (int r = g * 16; r < g * 16 + 16; ++r) {
;                         const bool sel = uu[r] > tau;
;                         const unsigned long long mk = __ballot(sel);
;                         const int pos = base + __builtin_amdgcn_mbcnt_hi((unsigned)(mk >> 32), __builtin_amdgcn_mbcnt_lo((unsigned)mk, 0));
;                         if (sel) myidx[pos] = r * 64 + lo;
;                         base += __popcll(mk);
;                         const unsigned long long me = __ballot(uu[r] == tau);
;                         if (me != 0ull) {
;                             const int epos = ebase + __builtin_amdgcn_mbcnt_hi((unsigned)(me >> 32), __builtin_amdgcn_mbcnt_lo((unsigned)me, 0));
;                             if (uu[r] == tau && epos < 256) myidx[epos] = r * 64 + lo;
;                             ebase += __popcll(me);
;                         }
.LBB0_1281:
	s_bcnt1_i32_b64 s4, s[14:15]
	s_add_i32 s18, s24, s4
	v_cmpx_lt_u32_e64 s[14:15], s26, v64
	s_nop 1
	s_lshl_b32 s4, s18, 2
	v_mbcnt_lo_u32_b32 v67, s14, 0
	s_add_i32 s4, s96, s4
	v_mbcnt_hi_u32_b32 v67, s15, v67
	v_add_u32_e32 v66, 0x1040, v65
	v_lshl_add_u32 v67, v67, 2, s4
	ds_write_b32 v67, v66
.LBB0_1283:
	s_mov_b64 exec, -1
	v_cmp_eq_u32_e32 vcc, s26, v64
	s_cbranch_vccz .LBB0_1287
	s_nop 0
	v_mbcnt_lo_u32_b32 v64, vcc_lo, 0
	v_mbcnt_hi_u32_b32 v64, vcc_hi, v64
	v_add_u32_e32 v64, s27, v64
	v_cmp_gt_i32_e64 s[16:17], s78, v64
	s_and_b64 s[4:5], vcc, s[16:17]
	s_and_saveexec_b64 s[16:17], s[4:5]
	v_add_u32_e32 v66, 0x1040, v65
	v_lshl_add_u32 v64, v64, 2, s96
	ds_write_b32 v64, v66
	s_or_b64 exec, exec, s[16:17]
	s_bcnt1_i32_b64 s4, vcc
	s_add_i32 s27, s27, s4
.LBB0_1287:
	s_bcnt1_i32_b64 s4, s[14:15]
	s_add_i32 s18, s18, s4
	v_cmpx_lt_u32_e64 s[14:15], s26, v63
	s_nop 1
	s_lshl_b32 s4, s18, 2
	v_mbcnt_lo_u32_b32 v66, s14, 0
	s_add_i32 s4, s96, s4
	v_mbcnt_hi_u32_b32 v66, s15, v66
	v_add_u32_e32 v64, 0x1080, v65
	v_lshl_add_u32 v66, v66, 2, s4
	ds_write_b32 v66, v64
.LBB0_1289:
	s_mov_b64 exec, -1
	v_cmp_eq_u32_e32 vcc, s26, v63
	s_cbranch_vccz .LBB0_1293
	s_nop 0
	v_mbcnt_lo_u32_b32 v63, vcc_lo, 0
	v_mbcnt_hi_u32_b32 v63, vcc_hi, v63
	v_add_u32_e32 v63, s27, v63
	v_cmp_gt_i32_e64 s[16:17], s78, v63
	s_and_b64 s[4:5], vcc, s[16:17]
	s_and_saveexec_b64 s[16:17], s[4:5]
	v_add_u32_e32 v64, 0x1080, v65
	v_lshl_add_u32 v63, v63, 2, s96
	ds_write_b32 v63, v64
	s_or_b64 exec, exec, s[16:17]
	s_bcnt1_i32_b64 s4, vcc
	s_add_i32 s27, s27, s4
.LBB0_1293:
	s_bcnt1_i32_b64 s4, s[14:15]
	s_add_i32 s18, s18, s4
	v_cmpx_lt_u32_e64 s[14:15], s26, v62
	s_nop 1
	s_lshl_b32 s4, s18, 2
	v_mbcnt_lo_u32_b32 v64, s14, 0
	s_add_i32 s4, s96, s4
	v_mbcnt_hi_u32_b32 v64, s15, v64
	v_add_u32_e32 v63, 0x10c0, v65
	v_lshl_add_u32 v64, v64, 2, s4
	ds_write_b32 v64, v63
.LBB0_1295:
	s_mov_b64 exec, -1
	v_cmp_eq_u32_e32 vcc, s26, v62
	s_cbranch_vccz .LBB0_1299
	s_nop 0
	v_mbcnt_lo_u32_b32 v62, vcc_lo, 0
	v_mbcnt_hi_u32_b32 v62, vcc_hi, v62
	v_add_u32_e32 v62, s27, v62
	v_cmp_gt_i32_e64 s[16:17], s78, v62
	s_and_b64 s[4:5], vcc, s[16:17]
	s_and_saveexec_b64 s[16:17], s[4:5]
	v_add_u32_e32 v63, 0x10c0, v65
	v_lshl_add_u32 v62, v62, 2, s96
	ds_write_b32 v62, v63
	s_or_b64 exec, exec, s[16:17]
	s_bcnt1_i32_b64 s4, vcc
	s_add_i32 s27, s27, s4
.LBB0_1299:
	s_bcnt1_i32_b64 s4, s[14:15]
	s_add_i32 s18, s18, s4
	v_cmpx_lt_u32_e64 s[14:15], s26, v61
	s_nop 1
	s_lshl_b32 s4, s18, 2
	v_mbcnt_lo_u32_b32 v63, s14, 0
	s_add_i32 s4, s96, s4
	v_mbcnt_hi_u32_b32 v63, s15, v63
	v_add_u32_e32 v62, 0x1100, v65
	v_lshl_add_u32 v63, v63, 2, s4
	ds_write_b32 v63, v62
.LBB0_1301:
	s_mov_b64 exec, -1
	v_cmp_eq_u32_e32 vcc, s26, v61
	s_cbranch_vccz .LBB0_1305
	s_nop 0
	v_mbcnt_lo_u32_b32 v61, vcc_lo, 0
	v_mbcnt_hi_u32_b32 v61, vcc_hi, v61
	v_add_u32_e32 v61, s27, v61
	v_cmp_gt_i32_e64 s[16:17], s78, v61
	s_and_b64 s[4:5], vcc, s[16:17]
	s_and_saveexec_b64 s[16:17], s[4:5]
	v_add_u32_e32 v62, 0x1100, v65
	v_lshl_add_u32 v61, v61, 2, s96
	ds_write_b32 v61, v62
	s_or_b64 exec, exec, s[16:17]
	s_bcnt1_i32_b64 s4, vcc
	s_add_i32 s27, s27, s4
.LBB0_1305:
	s_bcnt1_i32_b64 s4, s[14:15]
	s_add_i32 s18, s18, s4
	v_cmpx_lt_u32_e64 s[14:15], s26, v60
	s_nop 1
	s_lshl_b32 s4, s18, 2
	v_mbcnt_lo_u32_b32 v62, s14, 0
	s_add_i32 s4, s96, s4
	v_mbcnt_hi_u32_b32 v62, s15, v62
	v_add_u32_e32 v61, 0x1140, v65
	v_lshl_add_u32 v62, v62, 2, s4
	ds_write_b32 v62, v61
.LBB0_1307:
	s_mov_b64 exec, -1
	v_cmp_eq_u32_e32 vcc, s26, v60
	s_cbranch_vccz .LBB0_1311
	s_nop 0
	v_mbcnt_lo_u32_b32 v60, vcc_lo, 0
	v_mbcnt_hi_u32_b32 v60, vcc_hi, v60
	v_add_u32_e32 v60, s27, v60
	v_cmp_gt_i32_e64 s[16:17], s78, v60
	s_and_b64 s[4:5], vcc, s[16:17]
	s_and_saveexec_b64 s[16:17], s[4:5]
	v_add_u32_e32 v61, 0x1140, v65
	v_lshl_add_u32 v60, v60, 2, s96
	ds_write_b32 v60, v61
	s_or_b64 exec, exec, s[16:17]
	s_bcnt1_i32_b64 s4, vcc
	s_add_i32 s27, s27, s4
.LBB0_1311:
	s_bcnt1_i32_b64 s4, s[14:15]
	s_add_i32 s18, s18, s4
	v_cmpx_lt_u32_e64 s[14:15], s26, v59
	s_nop 1
	s_lshl_b32 s4, s18, 2
	v_mbcnt_lo_u32_b32 v61, s14, 0
	s_add_i32 s4, s96, s4
	v_mbcnt_hi_u32_b32 v61, s15, v61
	v_add_u32_e32 v60, 0x1180, v65
	v_lshl_add_u32 v61, v61, 2, s4
	ds_write_b32 v61, v60
.LBB0_1313:
	s_mov_b64 exec, -1
	v_cmp_eq_u32_e32 vcc, s26, v59
	s_cbranch_vccz .LBB0_1317
	s_nop 0
	v_mbcnt_lo_u32_b32 v59, vcc_lo, 0
	v_mbcnt_hi_u32_b32 v59, vcc_hi, v59
	v_add_u32_e32 v59, s27, v59
	v_cmp_gt_i32_e64 s[16:17], s78, v59
	s_and_b64 s[4:5], vcc, s[16:17]
	s_and_saveexec_b64 s[16:17], s[4:5]
	v_add_u32_e32 v60, 0x1180, v65
	v_lshl_add_u32 v59, v59, 2, s96
	ds_write_b32 v59, v60
	s_or_b64 exec, exec, s[16:17]
	s_bcnt1_i32_b64 s4, vcc
	s_add_i32 s27, s27, s4
.LBB0_1317:
	s_bcnt1_i32_b64 s4, s[14:15]
	s_add_i32 s18, s18, s4
	v_cmpx_lt_u32_e64 s[14:15], s26, v58
	s_nop 1
	s_lshl_b32 s4, s18, 2
	v_mbcnt_lo_u32_b32 v60, s14, 0
	s_add_i32 s4, s96, s4
	v_mbcnt_hi_u32_b32 v60, s15, v60
	v_add_u32_e32 v59, 0x11c0, v65
	v_lshl_add_u32 v60, v60, 2, s4
	ds_write_b32 v60, v59
.LBB0_1319:
	s_mov_b64 exec, -1
	v_cmp_eq_u32_e32 vcc, s26, v58
	s_cbranch_vccz .LBB0_1323
	s_nop 0
	v_mbcnt_lo_u32_b32 v58, vcc_lo, 0
	v_mbcnt_hi_u32_b32 v58, vcc_hi, v58
	v_add_u32_e32 v58, s27, v58
	v_cmp_gt_i32_e64 s[16:17], s78, v58
	s_and_b64 s[4:5], vcc, s[16:17]
	s_and_saveexec_b64 s[16:17], s[4:5]
	v_add_u32_e32 v59, 0x11c0, v65
	v_lshl_add_u32 v58, v58, 2, s96
	ds_write_b32 v58, v59
	s_or_b64 exec, exec, s[16:17]
	s_bcnt1_i32_b64 s4, vcc
	s_add_i32 s27, s27, s4
; __device__ __forceinline__ void dsa_tile(const Params& p, unsigned char* smem, int tile) {
;     ...
;                     for (int r = g * 16; r < g * 16 + 16; ++r) {
;                         const bool sel = uu[r] > tau;
;                         const unsigned long long mk = __ballot(sel);
;                         const int pos = base + __builtin_amdgcn_mbcnt_hi((unsigned)(mk >> 32), __builtin_amdgcn_mbcnt_lo((unsigned)mk, 0));
;                         if (sel) myidx[pos] = r * 64 + lo;
;                         base += __popcll(mk);
;                         const unsigned long long me = __ballot(uu[r] == tau);
;                         if (me != 0ull) {
;                             const int epos = ebase + __builtin_amdgcn_mbcnt_hi((unsigned)(me >> 32), __builtin_amdgcn_mbcnt_lo((unsigned)me, 0));
;                             if (uu[r] == tau && epos < 256) myidx[epos] = r * 64 + lo;
;                             ebase += __popcll(me);
;                         }
.LBB0_1323:
	s_bcnt1_i32_b64 s4, s[14:15]
	s_add_i32 s18, s18, s4
	v_cmpx_lt_u32_e64 s[14:15], s26, v57
	s_nop 1
	s_lshl_b32 s4, s18, 2
	v_mbcnt_lo_u32_b32 v59, s14, 0
	s_add_i32 s4, s96, s4
	v_mbcnt_hi_u32_b32 v59, s15, v59
	v_add_u32_e32 v58, 0x1200, v65
	v_lshl_add_u32 v59, v59, 2, s4
	ds_write_b32 v59, v58
.LBB0_1325:
	s_mov_b64 exec, -1
	v_cmp_eq_u32_e32 vcc, s26, v57
	s_cbranch_vccz .LBB0_1329
	s_nop 0
	v_mbcnt_lo_u32_b32 v57, vcc_lo, 0
	v_mbcnt_hi_u32_b32 v57, vcc_hi, v57
	v_add_u32_e32 v57, s27, v57
	v_cmp_gt_i32_e64 s[16:17], s78, v57
	s_and_b64 s[4:5], vcc, s[16:17]
	s_and_saveexec_b64 s[16:17], s[4:5]
	v_add_u32_e32 v58, 0x1200, v65
	v_lshl_add_u32 v57, v57, 2, s96
	ds_write_b32 v57, v58
	s_or_b64 exec, exec, s[16:17]
	s_bcnt1_i32_b64 s4, vcc
	s_add_i32 s27, s27, s4
.LBB0_1329:
	s_bcnt1_i32_b64 s4, s[14:15]
	s_add_i32 s18, s18, s4
	v_cmpx_lt_u32_e64 s[14:15], s26, v56
	s_nop 1
	s_lshl_b32 s4, s18, 2
	v_mbcnt_lo_u32_b32 v58, s14, 0
	s_add_i32 s4, s96, s4
	v_mbcnt_hi_u32_b32 v58, s15, v58
	v_add_u32_e32 v57, 0x1240, v65
	v_lshl_add_u32 v58, v58, 2, s4
	ds_write_b32 v58, v57
.LBB0_1331:
	s_mov_b64 exec, -1
	v_cmp_eq_u32_e32 vcc, s26, v56
	s_cbranch_vccz .LBB0_1335
	s_nop 0
	v_mbcnt_lo_u32_b32 v56, vcc_lo, 0
	v_mbcnt_hi_u32_b32 v56, vcc_hi, v56
	v_add_u32_e32 v56, s27, v56
	v_cmp_gt_i32_e64 s[16:17], s78, v56
	s_and_b64 s[4:5], vcc, s[16:17]
	s_and_saveexec_b64 s[16:17], s[4:5]
	v_add_u32_e32 v57, 0x1240, v65
	v_lshl_add_u32 v56, v56, 2, s96
	ds_write_b32 v56, v57
	s_or_b64 exec, exec, s[16:17]
	s_bcnt1_i32_b64 s4, vcc
	s_add_i32 s27, s27, s4
.LBB0_1335:
	s_bcnt1_i32_b64 s4, s[14:15]
	s_add_i32 s18, s18, s4
	v_cmpx_lt_u32_e64 s[14:15], s26, v55
	s_nop 1
	s_lshl_b32 s4, s18, 2
	v_mbcnt_lo_u32_b32 v57, s14, 0
	s_add_i32 s4, s96, s4
	v_mbcnt_hi_u32_b32 v57, s15, v57
	v_add_u32_e32 v56, 0x1280, v65
	v_lshl_add_u32 v57, v57, 2, s4
	ds_write_b32 v57, v56
.LBB0_1337:
	s_mov_b64 exec, -1
	v_cmp_eq_u32_e32 vcc, s26, v55
	s_cbranch_vccz .LBB0_1341
	s_nop 0
	v_mbcnt_lo_u32_b32 v55, vcc_lo, 0
	v_mbcnt_hi_u32_b32 v55, vcc_hi, v55
	v_add_u32_e32 v55, s27, v55
	v_cmp_gt_i32_e64 s[16:17], s78, v55
	s_and_b64 s[4:5], vcc, s[16:17]
	s_and_saveexec_b64 s[16:17], s[4:5]
	v_add_u32_e32 v56, 0x1280, v65
	v_lshl_add_u32 v55, v55, 2, s96
	ds_write_b32 v55, v56
	s_or_b64 exec, exec, s[16:17]
	s_bcnt1_i32_b64 s4, vcc
	s_add_i32 s27, s27, s4
.LBB0_1341:
	s_bcnt1_i32_b64 s4, s[14:15]
	s_add_i32 s18, s18, s4
	v_cmpx_lt_u32_e64 s[14:15], s26, v54
	s_nop 1
	s_lshl_b32 s4, s18, 2
	v_mbcnt_lo_u32_b32 v56, s14, 0
	s_add_i32 s4, s96, s4
	v_mbcnt_hi_u32_b32 v56, s15, v56
	v_add_u32_e32 v55, 0x12c0, v65
	v_lshl_add_u32 v56, v56, 2, s4
	ds_write_b32 v56, v55
.LBB0_1343:
	s_mov_b64 exec, -1
	v_cmp_eq_u32_e32 vcc, s26, v54
	s_cbranch_vccz .LBB0_1347
	s_nop 0
	v_mbcnt_lo_u32_b32 v54, vcc_lo, 0
	v_mbcnt_hi_u32_b32 v54, vcc_hi, v54
	v_add_u32_e32 v54, s27, v54
	v_cmp_gt_i32_e64 s[16:17], s78, v54
	s_and_b64 s[4:5], vcc, s[16:17]
	s_and_saveexec_b64 s[16:17], s[4:5]
	v_add_u32_e32 v55, 0x12c0, v65
	v_lshl_add_u32 v54, v54, 2, s96
	ds_write_b32 v54, v55
	s_or_b64 exec, exec, s[16:17]
	s_bcnt1_i32_b64 s4, vcc
	s_add_i32 s27, s27, s4
.LBB0_1347:
	s_bcnt1_i32_b64 s4, s[14:15]
	s_add_i32 s18, s18, s4
	v_cmpx_lt_u32_e64 s[14:15], s26, v53
	s_nop 1
	s_lshl_b32 s4, s18, 2
	v_mbcnt_lo_u32_b32 v55, s14, 0
	s_add_i32 s4, s96, s4
	v_mbcnt_hi_u32_b32 v55, s15, v55
	v_add_u32_e32 v54, 0x1300, v65
	v_lshl_add_u32 v55, v55, 2, s4
	ds_write_b32 v55, v54
.LBB0_1349:
	s_mov_b64 exec, -1
	v_cmp_eq_u32_e32 vcc, s26, v53
	s_cbranch_vccz .LBB0_1353
	s_nop 0
	v_mbcnt_lo_u32_b32 v53, vcc_lo, 0
	v_mbcnt_hi_u32_b32 v53, vcc_hi, v53
	v_add_u32_e32 v53, s27, v53
	v_cmp_gt_i32_e64 s[16:17], s78, v53
	s_and_b64 s[4:5], vcc, s[16:17]
	s_and_saveexec_b64 s[16:17], s[4:5]
	v_add_u32_e32 v54, 0x1300, v65
	v_lshl_add_u32 v53, v53, 2, s96
	ds_write_b32 v53, v54
	s_or_b64 exec, exec, s[16:17]
	s_bcnt1_i32_b64 s4, vcc
	s_add_i32 s27, s27, s4
.LBB0_1353:
	s_bcnt1_i32_b64 s4, s[14:15]
	s_add_i32 s18, s18, s4
	v_cmpx_lt_u32_e64 s[14:15], s26, v52
	s_nop 1
	s_lshl_b32 s4, s18, 2
	v_mbcnt_lo_u32_b32 v54, s14, 0
	s_add_i32 s4, s96, s4
	v_mbcnt_hi_u32_b32 v54, s15, v54
	v_add_u32_e32 v53, 0x1340, v65
	v_lshl_add_u32 v54, v54, 2, s4
	ds_write_b32 v54, v53
.LBB0_1355:
	s_mov_b64 exec, -1
	v_cmp_eq_u32_e32 vcc, s26, v52
	s_cbranch_vccz .LBB0_1359
	s_nop 0
	v_mbcnt_lo_u32_b32 v52, vcc_lo, 0
	v_mbcnt_hi_u32_b32 v52, vcc_hi, v52
	v_add_u32_e32 v52, s27, v52
	v_cmp_gt_i32_e64 s[16:17], s78, v52
	s_and_b64 s[4:5], vcc, s[16:17]
	s_and_saveexec_b64 s[16:17], s[4:5]
	v_add_u32_e32 v53, 0x1340, v65
	v_lshl_add_u32 v52, v52, 2, s96
	ds_write_b32 v52, v53
	s_or_b64 exec, exec, s[16:17]
	s_bcnt1_i32_b64 s4, vcc
	s_add_i32 s27, s27, s4
.LBB0_1359:
	s_bcnt1_i32_b64 s4, s[14:15]
	s_add_i32 s18, s18, s4
	v_cmpx_lt_u32_e64 s[14:15], s26, v51
	s_nop 1
	s_lshl_b32 s4, s18, 2
	v_mbcnt_lo_u32_b32 v53, s14, 0
	s_add_i32 s4, s96, s4
	v_mbcnt_hi_u32_b32 v53, s15, v53
	v_add_u32_e32 v52, 0x1380, v65
	v_lshl_add_u32 v53, v53, 2, s4
	ds_write_b32 v53, v52
.LBB0_1361:
	s_mov_b64 exec, -1
	v_cmp_eq_u32_e32 vcc, s26, v51
	s_cbranch_vccz .LBB0_1365
	s_nop 0
	v_mbcnt_lo_u32_b32 v51, vcc_lo, 0
	v_mbcnt_hi_u32_b32 v51, vcc_hi, v51
	v_add_u32_e32 v51, s27, v51
	v_cmp_gt_i32_e64 s[16:17], s78, v51
	s_and_b64 s[4:5], vcc, s[16:17]
	s_and_saveexec_b64 s[16:17], s[4:5]
	v_add_u32_e32 v52, 0x1380, v65
	v_lshl_add_u32 v51, v51, 2, s96
	ds_write_b32 v51, v52
	s_or_b64 exec, exec, s[16:17]
	s_bcnt1_i32_b64 s4, vcc
	s_add_i32 s27, s27, s4
.LBB0_1365:
	s_bcnt1_i32_b64 s4, s[14:15]
	s_add_i32 s18, s18, s4
	v_cmpx_lt_u32_e64 s[14:15], s26, v47
	s_nop 1
	s_lshl_b32 s4, s18, 2
	v_mbcnt_lo_u32_b32 v52, s14, 0
	s_add_i32 s4, s96, s4
	v_mbcnt_hi_u32_b32 v52, s15, v52
	v_add_u32_e32 v51, 0x13c0, v65
	v_lshl_add_u32 v52, v52, 2, s4
	ds_write_b32 v52, v51
.LBB0_1367:
	s_mov_b64 exec, -1
	v_cmp_eq_u32_e32 vcc, s26, v47
	s_cbranch_vccz .LBB0_1371
	s_nop 0
	v_mbcnt_lo_u32_b32 v47, vcc_lo, 0
	v_mbcnt_hi_u32_b32 v47, vcc_hi, v47
	v_add_u32_e32 v47, s27, v47
	v_cmp_gt_i32_e64 s[16:17], s78, v47
	s_and_b64 s[4:5], vcc, s[16:17]
	s_and_saveexec_b64 s[16:17], s[4:5]
	v_add_u32_e32 v51, 0x13c0, v65
	v_lshl_add_u32 v47, v47, 2, s96
	ds_write_b32 v47, v51
	s_or_b64 exec, exec, s[16:17]
	s_bcnt1_i32_b64 s4, vcc
	s_add_i32 s27, s27, s4

; __device__ __forceinline__ void dsa_tile(const Params& p, unsigned char* smem, int tile) {
;     ...
;                     for (int r = g * 16; r < g * 16 + 16; ++r) {
;                         const bool sel = uu[r] > tau;
;                         const unsigned long long mk = __ballot(sel);
;                         const int pos = base + __builtin_amdgcn_mbcnt_hi((unsigned)(mk >> 32), __builtin_amdgcn_mbcnt_lo((unsigned)mk, 0));
;                         if (sel) myidx[pos] = r * 64 + lo;
;                         base += __popcll(mk);
;                         const unsigned long long me = __ballot(uu[r] == tau);
;                         if (me != 0ull) {
;                             const int epos = ebase + __builtin_amdgcn_mbcnt_hi((unsigned)(me >> 32), __builtin_amdgcn_mbcnt_lo((unsigned)me, 0));
;                             if (uu[r] == tau && epos < 256) myidx[epos] = r * 64 + lo;
;                             ebase += __popcll(me);
;                         }
.LBB0_1378:
	s_bcnt1_i32_b64 s4, s[12:13]
	s_add_i32 s16, s24, s4
	v_cmpx_lt_u32_e64 s[12:13], s26, v49
	s_nop 1
	s_lshl_b32 s4, s16, 2
	v_mbcnt_lo_u32_b32 v51, s12, 0
	s_add_i32 s4, s96, s4
	v_mbcnt_hi_u32_b32 v51, s13, v51
	v_add_u32_e32 v50, 0x1440, v47
	v_lshl_add_u32 v51, v51, 2, s4
	ds_write_b32 v51, v50
.LBB0_1380:
	s_mov_b64 exec, -1
	v_cmp_eq_u32_e32 vcc, s26, v49
	s_cbranch_vccz .LBB0_1384
	s_nop 0
	v_mbcnt_lo_u32_b32 v49, vcc_lo, 0
	v_mbcnt_hi_u32_b32 v49, vcc_hi, v49
	v_add_u32_e32 v49, s27, v49
	v_cmp_gt_i32_e64 s[14:15], s78, v49
	s_and_b64 s[4:5], vcc, s[14:15]
	s_and_saveexec_b64 s[14:15], s[4:5]
	v_add_u32_e32 v50, 0x1440, v47
	v_lshl_add_u32 v49, v49, 2, s96
	ds_write_b32 v49, v50
	s_or_b64 exec, exec, s[14:15]
	s_bcnt1_i32_b64 s4, vcc
	s_add_i32 s27, s27, s4
.LBB0_1384:
	s_bcnt1_i32_b64 s4, s[12:13]
	s_add_i32 s16, s16, s4
	v_cmpx_lt_u32_e64 s[12:13], s26, v48
	s_nop 1
	s_lshl_b32 s4, s16, 2
	v_mbcnt_lo_u32_b32 v50, s12, 0
	s_add_i32 s4, s96, s4
	v_mbcnt_hi_u32_b32 v50, s13, v50
	v_add_u32_e32 v49, 0x1480, v47
	v_lshl_add_u32 v50, v50, 2, s4
	ds_write_b32 v50, v49
.LBB0_1386:
	s_mov_b64 exec, -1
	v_cmp_eq_u32_e32 vcc, s26, v48
	s_cbranch_vccz .LBB0_1390
	s_nop 0
	v_mbcnt_lo_u32_b32 v48, vcc_lo, 0
	v_mbcnt_hi_u32_b32 v48, vcc_hi, v48
	v_add_u32_e32 v48, s27, v48
	v_cmp_gt_i32_e64 s[14:15], s78, v48
	s_and_b64 s[4:5], vcc, s[14:15]
	s_and_saveexec_b64 s[14:15], s[4:5]
	v_add_u32_e32 v49, 0x1480, v47
	v_lshl_add_u32 v48, v48, 2, s96
	ds_write_b32 v48, v49
	s_or_b64 exec, exec, s[14:15]
	s_bcnt1_i32_b64 s4, vcc
	s_add_i32 s27, s27, s4
.LBB0_1390:
	s_bcnt1_i32_b64 s4, s[12:13]
	s_add_i32 s16, s16, s4
	v_cmpx_lt_u32_e64 s[12:13], s26, v46
	s_nop 1
	s_lshl_b32 s4, s16, 2
	v_mbcnt_lo_u32_b32 v49, s12, 0
	s_add_i32 s4, s96, s4
	v_mbcnt_hi_u32_b32 v49, s13, v49
	v_add_u32_e32 v48, 0x14c0, v47
	v_lshl_add_u32 v49, v49, 2, s4
	ds_write_b32 v49, v48
.LBB0_1392:
	s_mov_b64 exec, -1
	v_cmp_eq_u32_e32 vcc, s26, v46
	s_cbranch_vccz .LBB0_1396
	s_nop 0
	v_mbcnt_lo_u32_b32 v46, vcc_lo, 0
	v_mbcnt_hi_u32_b32 v46, vcc_hi, v46
	v_add_u32_e32 v46, s27, v46
	v_cmp_gt_i32_e64 s[14:15], s78, v46
	s_and_b64 s[4:5], vcc, s[14:15]
	s_and_saveexec_b64 s[14:15], s[4:5]
	v_add_u32_e32 v48, 0x14c0, v47
	v_lshl_add_u32 v46, v46, 2, s96
	ds_write_b32 v46, v48
	s_or_b64 exec, exec, s[14:15]
	s_bcnt1_i32_b64 s4, vcc
	s_add_i32 s27, s27, s4
.LBB0_1396:
	s_bcnt1_i32_b64 s4, s[12:13]
	s_add_i32 s16, s16, s4
	v_cmpx_lt_u32_e64 s[12:13], s26, v45
	s_nop 1
	s_lshl_b32 s4, s16, 2
	v_mbcnt_lo_u32_b32 v48, s12, 0
	s_add_i32 s4, s96, s4
	v_mbcnt_hi_u32_b32 v48, s13, v48
	v_add_u32_e32 v46, 0x1500, v47
	v_lshl_add_u32 v48, v48, 2, s4
	ds_write_b32 v48, v46
.LBB0_1398:
	s_mov_b64 exec, -1
	v_cmp_eq_u32_e32 vcc, s26, v45
	s_cbranch_vccz .LBB0_1402
	s_nop 0
	v_mbcnt_lo_u32_b32 v45, vcc_lo, 0
	v_mbcnt_hi_u32_b32 v45, vcc_hi, v45
	v_add_u32_e32 v45, s27, v45
	v_cmp_gt_i32_e64 s[14:15], s78, v45
	s_and_b64 s[4:5], vcc, s[14:15]
	s_and_saveexec_b64 s[14:15], s[4:5]
	v_add_u32_e32 v46, 0x1500, v47
	v_lshl_add_u32 v45, v45, 2, s96
	ds_write_b32 v45, v46
	s_or_b64 exec, exec, s[14:15]
	s_bcnt1_i32_b64 s4, vcc
	s_add_i32 s27, s27, s4
.LBB0_1402:
	s_bcnt1_i32_b64 s4, s[12:13]
	s_add_i32 s16, s16, s4
	v_cmpx_lt_u32_e64 s[12:13], s26, v44
	s_nop 1
	s_lshl_b32 s4, s16, 2
	v_mbcnt_lo_u32_b32 v46, s12, 0
	s_add_i32 s4, s96, s4
	v_mbcnt_hi_u32_b32 v46, s13, v46
	v_add_u32_e32 v45, 0x1540, v47
	v_lshl_add_u32 v46, v46, 2, s4
	ds_write_b32 v46, v45
.LBB0_1404:
	s_mov_b64 exec, -1
	v_cmp_eq_u32_e32 vcc, s26, v44
	s_cbranch_vccz .LBB0_1408
	s_nop 0
	v_mbcnt_lo_u32_b32 v44, vcc_lo, 0
	v_mbcnt_hi_u32_b32 v44, vcc_hi, v44
	v_add_u32_e32 v44, s27, v44
	v_cmp_gt_i32_e64 s[14:15], s78, v44
	s_and_b64 s[4:5], vcc, s[14:15]
	s_and_saveexec_b64 s[14:15], s[4:5]
	v_add_u32_e32 v45, 0x1540, v47
	v_lshl_add_u32 v44, v44, 2, s96
	ds_write_b32 v44, v45
	s_or_b64 exec, exec, s[14:15]
	s_bcnt1_i32_b64 s4, vcc
	s_add_i32 s27, s27, s4
.LBB0_1408:
	s_bcnt1_i32_b64 s4, s[12:13]
	s_add_i32 s16, s16, s4
	v_cmpx_lt_u32_e64 s[12:13], s26, v43
	s_nop 1
	s_lshl_b32 s4, s16, 2
	v_mbcnt_lo_u32_b32 v45, s12, 0
	s_add_i32 s4, s96, s4
	v_mbcnt_hi_u32_b32 v45, s13, v45
	v_add_u32_e32 v44, 0x1580, v47
	v_lshl_add_u32 v45, v45, 2, s4
	ds_write_b32 v45, v44
.LBB0_1410:
	s_mov_b64 exec, -1
	v_cmp_eq_u32_e32 vcc, s26, v43
	s_cbranch_vccz .LBB0_1414
	s_nop 0
	v_mbcnt_lo_u32_b32 v43, vcc_lo, 0
	v_mbcnt_hi_u32_b32 v43, vcc_hi, v43
	v_add_u32_e32 v43, s27, v43
	v_cmp_gt_i32_e64 s[14:15], s78, v43
	s_and_b64 s[4:5], vcc, s[14:15]
	s_and_saveexec_b64 s[14:15], s[4:5]
	v_add_u32_e32 v44, 0x1580, v47
	v_lshl_add_u32 v43, v43, 2, s96
	ds_write_b32 v43, v44
	s_or_b64 exec, exec, s[14:15]
	s_bcnt1_i32_b64 s4, vcc
	s_add_i32 s27, s27, s4
.LBB0_1414:
	s_bcnt1_i32_b64 s4, s[12:13]
	s_add_i32 s16, s16, s4
	v_cmpx_lt_u32_e64 s[12:13], s26, v42
	s_nop 1
	s_lshl_b32 s4, s16, 2
	v_mbcnt_lo_u32_b32 v44, s12, 0
	s_add_i32 s4, s96, s4
	v_mbcnt_hi_u32_b32 v44, s13, v44
	v_add_u32_e32 v43, 0x15c0, v47
	v_lshl_add_u32 v44, v44, 2, s4
	ds_write_b32 v44, v43
.LBB0_1416:
	s_mov_b64 exec, -1
	v_cmp_eq_u32_e32 vcc, s26, v42
	s_cbranch_vccz .LBB0_1420
	s_nop 0
	v_mbcnt_lo_u32_b32 v42, vcc_lo, 0
	v_mbcnt_hi_u32_b32 v42, vcc_hi, v42
	v_add_u32_e32 v42, s27, v42
	v_cmp_gt_i32_e64 s[14:15], s78, v42
	s_and_b64 s[4:5], vcc, s[14:15]
	s_and_saveexec_b64 s[14:15], s[4:5]
	v_add_u32_e32 v43, 0x15c0, v47
	v_lshl_add_u32 v42, v42, 2, s96
	ds_write_b32 v42, v43
	s_or_b64 exec, exec, s[14:15]
	s_bcnt1_i32_b64 s4, vcc
	s_add_i32 s27, s27, s4
; __device__ __forceinline__ void dsa_tile(const Params& p, unsigned char* smem, int tile) {
;     ...
;                     for (int r = g * 16; r < g * 16 + 16; ++r) {
;                         const bool sel = uu[r] > tau;
;                         const unsigned long long mk = __ballot(sel);
;                         const int pos = base + __builtin_amdgcn_mbcnt_hi((unsigned)(mk >> 32), __builtin_amdgcn_mbcnt_lo((unsigned)mk, 0));
;                         if (sel) myidx[pos] = r * 64 + lo;
;                         base += __popcll(mk);
;                         const unsigned long long me = __ballot(uu[r] == tau);
;                         if (me != 0ull) {
;                             const int epos = ebase + __builtin_amdgcn_mbcnt_hi((unsigned)(me >> 32), __builtin_amdgcn_mbcnt_lo((unsigned)me, 0));
;                             if (uu[r] == tau && epos < 256) myidx[epos] = r * 64 + lo;
;                             ebase += __popcll(me);
;                         }
.LBB0_1420:
	s_bcnt1_i32_b64 s4, s[12:13]
	s_add_i32 s16, s16, s4
	v_cmpx_lt_u32_e64 s[12:13], s26, v41
	s_nop 1
	s_lshl_b32 s4, s16, 2
	v_mbcnt_lo_u32_b32 v43, s12, 0
	s_add_i32 s4, s96, s4
	v_mbcnt_hi_u32_b32 v43, s13, v43
	v_add_u32_e32 v42, 0x1600, v47
	v_lshl_add_u32 v43, v43, 2, s4
	ds_write_b32 v43, v42
.LBB0_1422:
	s_mov_b64 exec, -1
	v_cmp_eq_u32_e32 vcc, s26, v41
	s_cbranch_vccz .LBB0_1426
	s_nop 0
	v_mbcnt_lo_u32_b32 v41, vcc_lo, 0
	v_mbcnt_hi_u32_b32 v41, vcc_hi, v41
	v_add_u32_e32 v41, s27, v41
	v_cmp_gt_i32_e64 s[14:15], s78, v41
	s_and_b64 s[4:5], vcc, s[14:15]
	s_and_saveexec_b64 s[14:15], s[4:5]
	v_add_u32_e32 v42, 0x1600, v47
	v_lshl_add_u32 v41, v41, 2, s96
	ds_write_b32 v41, v42
	s_or_b64 exec, exec, s[14:15]
	s_bcnt1_i32_b64 s4, vcc
	s_add_i32 s27, s27, s4
.LBB0_1426:
	s_bcnt1_i32_b64 s4, s[12:13]
	s_add_i32 s16, s16, s4
	v_cmpx_lt_u32_e64 s[12:13], s26, v40
	s_nop 1
	s_lshl_b32 s4, s16, 2
	v_mbcnt_lo_u32_b32 v42, s12, 0
	s_add_i32 s4, s96, s4
	v_mbcnt_hi_u32_b32 v42, s13, v42
	v_add_u32_e32 v41, 0x1640, v47
	v_lshl_add_u32 v42, v42, 2, s4
	ds_write_b32 v42, v41
.LBB0_1428:
	s_mov_b64 exec, -1
	v_cmp_eq_u32_e32 vcc, s26, v40
	s_cbranch_vccz .LBB0_1432
	s_nop 0
	v_mbcnt_lo_u32_b32 v40, vcc_lo, 0
	v_mbcnt_hi_u32_b32 v40, vcc_hi, v40
	v_add_u32_e32 v40, s27, v40
	v_cmp_gt_i32_e64 s[14:15], s78, v40
	s_and_b64 s[4:5], vcc, s[14:15]
	s_and_saveexec_b64 s[14:15], s[4:5]
	v_add_u32_e32 v41, 0x1640, v47
	v_lshl_add_u32 v40, v40, 2, s96
	ds_write_b32 v40, v41
	s_or_b64 exec, exec, s[14:15]
	s_bcnt1_i32_b64 s4, vcc
	s_add_i32 s27, s27, s4
.LBB0_1432:
	s_bcnt1_i32_b64 s4, s[12:13]
	s_add_i32 s16, s16, s4
	v_cmpx_lt_u32_e64 s[12:13], s26, v39
	s_nop 1
	s_lshl_b32 s4, s16, 2
	v_mbcnt_lo_u32_b32 v41, s12, 0
	s_add_i32 s4, s96, s4
	v_mbcnt_hi_u32_b32 v41, s13, v41
	v_add_u32_e32 v40, 0x1680, v47
	v_lshl_add_u32 v41, v41, 2, s4
	ds_write_b32 v41, v40
.LBB0_1434:
	s_mov_b64 exec, -1
	v_cmp_eq_u32_e32 vcc, s26, v39
	s_cbranch_vccz .LBB0_1438
	s_nop 0
	v_mbcnt_lo_u32_b32 v39, vcc_lo, 0
	v_mbcnt_hi_u32_b32 v39, vcc_hi, v39
	v_add_u32_e32 v39, s27, v39
	v_cmp_gt_i32_e64 s[14:15], s78, v39
	s_and_b64 s[4:5], vcc, s[14:15]
	s_and_saveexec_b64 s[14:15], s[4:5]
	v_add_u32_e32 v40, 0x1680, v47
	v_lshl_add_u32 v39, v39, 2, s96
	ds_write_b32 v39, v40
	s_or_b64 exec, exec, s[14:15]
	s_bcnt1_i32_b64 s4, vcc
	s_add_i32 s27, s27, s4
.LBB0_1438:
	s_bcnt1_i32_b64 s4, s[12:13]
	s_add_i32 s16, s16, s4
	v_cmpx_lt_u32_e64 s[12:13], s26, v38
	s_nop 1
	s_lshl_b32 s4, s16, 2
	v_mbcnt_lo_u32_b32 v40, s12, 0
	s_add_i32 s4, s96, s4
	v_mbcnt_hi_u32_b32 v40, s13, v40
	v_add_u32_e32 v39, 0x16c0, v47
	v_lshl_add_u32 v40, v40, 2, s4
	ds_write_b32 v40, v39
.LBB0_1440:
	s_mov_b64 exec, -1
	v_cmp_eq_u32_e32 vcc, s26, v38
	s_cbranch_vccz .LBB0_1444
	s_nop 0
	v_mbcnt_lo_u32_b32 v38, vcc_lo, 0
	v_mbcnt_hi_u32_b32 v38, vcc_hi, v38
	v_add_u32_e32 v38, s27, v38
	v_cmp_gt_i32_e64 s[14:15], s78, v38
	s_and_b64 s[4:5], vcc, s[14:15]
	s_and_saveexec_b64 s[14:15], s[4:5]
	v_add_u32_e32 v39, 0x16c0, v47
	v_lshl_add_u32 v38, v38, 2, s96
	ds_write_b32 v38, v39
	s_or_b64 exec, exec, s[14:15]
	s_bcnt1_i32_b64 s4, vcc
	s_add_i32 s27, s27, s4
.LBB0_1444:
	s_bcnt1_i32_b64 s4, s[12:13]
	s_add_i32 s16, s16, s4
	v_cmpx_lt_u32_e64 s[12:13], s26, v37
	s_nop 1
	s_lshl_b32 s4, s16, 2
	v_mbcnt_lo_u32_b32 v39, s12, 0
	s_add_i32 s4, s96, s4
	v_mbcnt_hi_u32_b32 v39, s13, v39
	v_add_u32_e32 v38, 0x1700, v47
	v_lshl_add_u32 v39, v39, 2, s4
	ds_write_b32 v39, v38
.LBB0_1446:
	s_mov_b64 exec, -1
	v_cmp_eq_u32_e32 vcc, s26, v37
	s_cbranch_vccz .LBB0_1450
	s_nop 0
	v_mbcnt_lo_u32_b32 v37, vcc_lo, 0
	v_mbcnt_hi_u32_b32 v37, vcc_hi, v37
	v_add_u32_e32 v37, s27, v37
	v_cmp_gt_i32_e64 s[14:15], s78, v37
	s_and_b64 s[4:5], vcc, s[14:15]
	s_and_saveexec_b64 s[14:15], s[4:5]
	v_add_u32_e32 v38, 0x1700, v47
	v_lshl_add_u32 v37, v37, 2, s96
	ds_write_b32 v37, v38
	s_or_b64 exec, exec, s[14:15]
	s_bcnt1_i32_b64 s4, vcc
	s_add_i32 s27, s27, s4
.LBB0_1450:
	s_bcnt1_i32_b64 s4, s[12:13]
	s_add_i32 s16, s16, s4
	v_cmpx_lt_u32_e64 s[12:13], s26, v36
	s_nop 1
	s_lshl_b32 s4, s16, 2
	v_mbcnt_lo_u32_b32 v38, s12, 0
	s_add_i32 s4, s96, s4
	v_mbcnt_hi_u32_b32 v38, s13, v38
	v_add_u32_e32 v37, 0x1740, v47
	v_lshl_add_u32 v38, v38, 2, s4
	ds_write_b32 v38, v37
.LBB0_1452:
	s_mov_b64 exec, -1
	v_cmp_eq_u32_e32 vcc, s26, v36
	s_cbranch_vccz .LBB0_1456
	s_nop 0
	v_mbcnt_lo_u32_b32 v36, vcc_lo, 0
	v_mbcnt_hi_u32_b32 v36, vcc_hi, v36
	v_add_u32_e32 v36, s27, v36
	v_cmp_gt_i32_e64 s[14:15], s78, v36
	s_and_b64 s[4:5], vcc, s[14:15]
	s_and_saveexec_b64 s[14:15], s[4:5]
	v_add_u32_e32 v37, 0x1740, v47
	v_lshl_add_u32 v36, v36, 2, s96
	ds_write_b32 v36, v37
	s_or_b64 exec, exec, s[14:15]
	s_bcnt1_i32_b64 s4, vcc
	s_add_i32 s27, s27, s4
.LBB0_1456:
	s_bcnt1_i32_b64 s4, s[12:13]
	s_add_i32 s16, s16, s4
	v_cmpx_lt_u32_e64 s[12:13], s26, v35
	s_nop 1
	s_lshl_b32 s4, s16, 2
	v_mbcnt_lo_u32_b32 v37, s12, 0
	s_add_i32 s4, s96, s4
	v_mbcnt_hi_u32_b32 v37, s13, v37
	v_add_u32_e32 v36, 0x1780, v47
	v_lshl_add_u32 v37, v37, 2, s4
	ds_write_b32 v37, v36
.LBB0_1458:
	s_mov_b64 exec, -1
	v_cmp_eq_u32_e32 vcc, s26, v35
	s_cbranch_vccz .LBB0_1462
	s_nop 0
	v_mbcnt_lo_u32_b32 v35, vcc_lo, 0
	v_mbcnt_hi_u32_b32 v35, vcc_hi, v35
	v_add_u32_e32 v35, s27, v35
	v_cmp_gt_i32_e64 s[14:15], s78, v35
	s_and_b64 s[4:5], vcc, s[14:15]
	s_and_saveexec_b64 s[14:15], s[4:5]
	v_add_u32_e32 v36, 0x1780, v47
	v_lshl_add_u32 v35, v35, 2, s96
	ds_write_b32 v35, v36
	s_or_b64 exec, exec, s[14:15]
	s_bcnt1_i32_b64 s4, vcc
	s_add_i32 s27, s27, s4
.LBB0_1462:
	s_bcnt1_i32_b64 s4, s[12:13]
	s_add_i32 s16, s16, s4
	v_cmpx_lt_u32_e64 s[12:13], s26, v33
	s_nop 1
	s_lshl_b32 s4, s16, 2
	v_mbcnt_lo_u32_b32 v36, s12, 0
	s_add_i32 s4, s96, s4
	v_mbcnt_hi_u32_b32 v36, s13, v36
	v_add_u32_e32 v35, 0x17c0, v47
	v_lshl_add_u32 v36, v36, 2, s4
	ds_write_b32 v36, v35
.LBB0_1464:
	s_mov_b64 exec, -1
	v_cmp_eq_u32_e32 vcc, s26, v33
	s_cbranch_vccz .LBB0_1468
	s_nop 0
	v_mbcnt_lo_u32_b32 v33, vcc_lo, 0
	v_mbcnt_hi_u32_b32 v33, vcc_hi, v33
	v_add_u32_e32 v33, s27, v33
	v_cmp_gt_i32_e64 s[14:15], s78, v33
	s_and_b64 s[4:5], vcc, s[14:15]
	s_and_saveexec_b64 s[14:15], s[4:5]
	v_add_u32_e32 v35, 0x17c0, v47
	v_lshl_add_u32 v33, v33, 2, s96
	ds_write_b32 v33, v35
	s_or_b64 exec, exec, s[14:15]
	s_bcnt1_i32_b64 s4, vcc
	s_add_i32 s27, s27, s4

; __device__ __forceinline__ void dsa_tile(const Params& p, unsigned char* smem, int tile) {
;     ...
;                     for (int r = g * 16; r < g * 16 + 16; ++r) {
;                         const bool sel = uu[r] > tau;
;                         const unsigned long long mk = __ballot(sel);
;                         const int pos = base + __builtin_amdgcn_mbcnt_hi((unsigned)(mk >> 32), __builtin_amdgcn_mbcnt_lo((unsigned)mk, 0));
;                         if (sel) myidx[pos] = r * 64 + lo;
;                         base += __popcll(mk);
;                         const unsigned long long me = __ballot(uu[r] == tau);
;                         if (me != 0ull) {
;                             const int epos = ebase + __builtin_amdgcn_mbcnt_hi((unsigned)(me >> 32), __builtin_amdgcn_mbcnt_lo((unsigned)me, 0));
;                             if (uu[r] == tau && epos < 256) myidx[epos] = r * 64 + lo;
;                             ebase += __popcll(me);
;                         }
.LBB0_1475:
	s_bcnt1_i32_b64 s4, s[10:11]
	s_add_i32 s14, s24, s4
	v_cmpx_lt_u32_e64 s[10:11], s26, v32
	s_nop 1
	s_lshl_b32 s4, s14, 2
	v_mbcnt_lo_u32_b32 v35, s10, 0
	s_add_i32 s4, s96, s4
	v_mbcnt_hi_u32_b32 v35, s11, v35
	v_add_u32_e32 v34, 0x1840, v33
	v_lshl_add_u32 v35, v35, 2, s4
	ds_write_b32 v35, v34
.LBB0_1477:
	s_mov_b64 exec, -1
	v_cmp_eq_u32_e32 vcc, s26, v32
	s_cbranch_vccz .LBB0_1481
	s_nop 0
	v_mbcnt_lo_u32_b32 v32, vcc_lo, 0
	v_mbcnt_hi_u32_b32 v32, vcc_hi, v32
	v_add_u32_e32 v32, s27, v32
	v_cmp_gt_i32_e64 s[12:13], s78, v32
	s_and_b64 s[4:5], vcc, s[12:13]
	s_and_saveexec_b64 s[12:13], s[4:5]
	v_add_u32_e32 v34, 0x1840, v33
	v_lshl_add_u32 v32, v32, 2, s96
	ds_write_b32 v32, v34
	s_or_b64 exec, exec, s[12:13]
	s_bcnt1_i32_b64 s4, vcc
	s_add_i32 s27, s27, s4
.LBB0_1481:
	s_bcnt1_i32_b64 s4, s[10:11]
	s_add_i32 s14, s14, s4
	v_cmpx_lt_u32_e64 s[10:11], s26, v31
	s_nop 1
	s_lshl_b32 s4, s14, 2
	v_mbcnt_lo_u32_b32 v34, s10, 0
	s_add_i32 s4, s96, s4
	v_mbcnt_hi_u32_b32 v34, s11, v34
	v_add_u32_e32 v32, 0x1880, v33
	v_lshl_add_u32 v34, v34, 2, s4
	ds_write_b32 v34, v32
.LBB0_1483:
	s_mov_b64 exec, -1
	v_cmp_eq_u32_e32 vcc, s26, v31
	s_cbranch_vccz .LBB0_1487
	s_nop 0
	v_mbcnt_lo_u32_b32 v31, vcc_lo, 0
	v_mbcnt_hi_u32_b32 v31, vcc_hi, v31
	v_add_u32_e32 v31, s27, v31
	v_cmp_gt_i32_e64 s[12:13], s78, v31
	s_and_b64 s[4:5], vcc, s[12:13]
	s_and_saveexec_b64 s[12:13], s[4:5]
	v_add_u32_e32 v32, 0x1880, v33
	v_lshl_add_u32 v31, v31, 2, s96
	ds_write_b32 v31, v32
	s_or_b64 exec, exec, s[12:13]
	s_bcnt1_i32_b64 s4, vcc
	s_add_i32 s27, s27, s4
.LBB0_1487:
	s_bcnt1_i32_b64 s4, s[10:11]
	s_add_i32 s14, s14, s4
	v_cmpx_lt_u32_e64 s[10:11], s26, v30
	s_nop 1
	s_lshl_b32 s4, s14, 2
	v_mbcnt_lo_u32_b32 v32, s10, 0
	s_add_i32 s4, s96, s4
	v_mbcnt_hi_u32_b32 v32, s11, v32
	v_add_u32_e32 v31, 0x18c0, v33
	v_lshl_add_u32 v32, v32, 2, s4
	ds_write_b32 v32, v31
.LBB0_1489:
	s_mov_b64 exec, -1
	v_cmp_eq_u32_e32 vcc, s26, v30
	s_cbranch_vccz .LBB0_1493
	s_nop 0
	v_mbcnt_lo_u32_b32 v30, vcc_lo, 0
	v_mbcnt_hi_u32_b32 v30, vcc_hi, v30
	v_add_u32_e32 v30, s27, v30
	v_cmp_gt_i32_e64 s[12:13], s78, v30
	s_and_b64 s[4:5], vcc, s[12:13]
	s_and_saveexec_b64 s[12:13], s[4:5]
	v_add_u32_e32 v31, 0x18c0, v33
	v_lshl_add_u32 v30, v30, 2, s96
	ds_write_b32 v30, v31
	s_or_b64 exec, exec, s[12:13]
	s_bcnt1_i32_b64 s4, vcc
	s_add_i32 s27, s27, s4
.LBB0_1493:
	s_bcnt1_i32_b64 s4, s[10:11]
	s_add_i32 s14, s14, s4
	v_cmpx_lt_u32_e64 s[10:11], s26, v29
	s_nop 1
	s_lshl_b32 s4, s14, 2
	v_mbcnt_lo_u32_b32 v31, s10, 0
	s_add_i32 s4, s96, s4
	v_mbcnt_hi_u32_b32 v31, s11, v31
	v_add_u32_e32 v30, 0x1900, v33
	v_lshl_add_u32 v31, v31, 2, s4
	ds_write_b32 v31, v30
.LBB0_1495:
	s_mov_b64 exec, -1
	v_cmp_eq_u32_e32 vcc, s26, v29
	s_cbranch_vccz .LBB0_1499
	s_nop 0
	v_mbcnt_lo_u32_b32 v29, vcc_lo, 0
	v_mbcnt_hi_u32_b32 v29, vcc_hi, v29
	v_add_u32_e32 v29, s27, v29
	v_cmp_gt_i32_e64 s[12:13], s78, v29
	s_and_b64 s[4:5], vcc, s[12:13]
	s_and_saveexec_b64 s[12:13], s[4:5]
	v_add_u32_e32 v30, 0x1900, v33
	v_lshl_add_u32 v29, v29, 2, s96
	ds_write_b32 v29, v30
	s_or_b64 exec, exec, s[12:13]
	s_bcnt1_i32_b64 s4, vcc
	s_add_i32 s27, s27, s4
.LBB0_1499:
	s_bcnt1_i32_b64 s4, s[10:11]
	s_add_i32 s14, s14, s4
	v_cmpx_lt_u32_e64 s[10:11], s26, v28
	s_nop 1
	s_lshl_b32 s4, s14, 2
	v_mbcnt_lo_u32_b32 v30, s10, 0
	s_add_i32 s4, s96, s4
	v_mbcnt_hi_u32_b32 v30, s11, v30
	v_add_u32_e32 v29, 0x1940, v33
	v_lshl_add_u32 v30, v30, 2, s4
	ds_write_b32 v30, v29
.LBB0_1501:
	s_mov_b64 exec, -1
	v_cmp_eq_u32_e32 vcc, s26, v28
	s_cbranch_vccz .LBB0_1505
	s_nop 0
	v_mbcnt_lo_u32_b32 v28, vcc_lo, 0
	v_mbcnt_hi_u32_b32 v28, vcc_hi, v28
	v_add_u32_e32 v28, s27, v28
	v_cmp_gt_i32_e64 s[12:13], s78, v28
	s_and_b64 s[4:5], vcc, s[12:13]
	s_and_saveexec_b64 s[12:13], s[4:5]
	v_add_u32_e32 v29, 0x1940, v33
	v_lshl_add_u32 v28, v28, 2, s96
	ds_write_b32 v28, v29
	s_or_b64 exec, exec, s[12:13]
	s_bcnt1_i32_b64 s4, vcc
	s_add_i32 s27, s27, s4
.LBB0_1505:
	s_bcnt1_i32_b64 s4, s[10:11]
	s_add_i32 s14, s14, s4
	v_cmpx_lt_u32_e64 s[10:11], s26, v27
	s_nop 1
	s_lshl_b32 s4, s14, 2
	v_mbcnt_lo_u32_b32 v29, s10, 0
	s_add_i32 s4, s96, s4
	v_mbcnt_hi_u32_b32 v29, s11, v29
	v_add_u32_e32 v28, 0x1980, v33
	v_lshl_add_u32 v29, v29, 2, s4
	ds_write_b32 v29, v28
.LBB0_1507:
	s_mov_b64 exec, -1
	v_cmp_eq_u32_e32 vcc, s26, v27
	s_cbranch_vccz .LBB0_1511
	s_nop 0
	v_mbcnt_lo_u32_b32 v27, vcc_lo, 0
	v_mbcnt_hi_u32_b32 v27, vcc_hi, v27
	v_add_u32_e32 v27, s27, v27
	v_cmp_gt_i32_e64 s[12:13], s78, v27
	s_and_b64 s[4:5], vcc, s[12:13]
	s_and_saveexec_b64 s[12:13], s[4:5]
	v_add_u32_e32 v28, 0x1980, v33
	v_lshl_add_u32 v27, v27, 2, s96
	ds_write_b32 v27, v28
	s_or_b64 exec, exec, s[12:13]
	s_bcnt1_i32_b64 s4, vcc
	s_add_i32 s27, s27, s4
.LBB0_1511:
	s_bcnt1_i32_b64 s4, s[10:11]
	s_add_i32 s14, s14, s4
	v_cmpx_lt_u32_e64 s[10:11], s26, v26
	s_nop 1
	s_lshl_b32 s4, s14, 2
	v_mbcnt_lo_u32_b32 v28, s10, 0
	s_add_i32 s4, s96, s4
	v_mbcnt_hi_u32_b32 v28, s11, v28
	v_add_u32_e32 v27, 0x19c0, v33
	v_lshl_add_u32 v28, v28, 2, s4
	ds_write_b32 v28, v27
.LBB0_1513:
	s_mov_b64 exec, -1
	v_cmp_eq_u32_e32 vcc, s26, v26
	s_cbranch_vccz .LBB0_1517
	s_nop 0
	v_mbcnt_lo_u32_b32 v26, vcc_lo, 0
	v_mbcnt_hi_u32_b32 v26, vcc_hi, v26
	v_add_u32_e32 v26, s27, v26
	v_cmp_gt_i32_e64 s[12:13], s78, v26
	s_and_b64 s[4:5], vcc, s[12:13]
	s_and_saveexec_b64 s[12:13], s[4:5]
	v_add_u32_e32 v27, 0x19c0, v33
	v_lshl_add_u32 v26, v26, 2, s96
	ds_write_b32 v26, v27
	s_or_b64 exec, exec, s[12:13]
	s_bcnt1_i32_b64 s4, vcc
	s_add_i32 s27, s27, s4
; __device__ __forceinline__ void dsa_tile(const Params& p, unsigned char* smem, int tile) {
;     ...
;                     for (int r = g * 16; r < g * 16 + 16; ++r) {
;                         const bool sel = uu[r] > tau;
;                         const unsigned long long mk = __ballot(sel);
;                         const int pos = base + __builtin_amdgcn_mbcnt_hi((unsigned)(mk >> 32), __builtin_amdgcn_mbcnt_lo((unsigned)mk, 0));
;                         if (sel) myidx[pos] = r * 64 + lo;
;                         base += __popcll(mk);
;                         const unsigned long long me = __ballot(uu[r] == tau);
;                         if (me != 0ull) {
;                             const int epos = ebase + __builtin_amdgcn_mbcnt_hi((unsigned)(me >> 32), __builtin_amdgcn_mbcnt_lo((unsigned)me, 0));
;                             if (uu[r] == tau && epos < 256) myidx[epos] = r * 64 + lo;
;                             ebase += __popcll(me);
;                         }
.LBB0_1517:
	s_bcnt1_i32_b64 s4, s[10:11]
	s_add_i32 s14, s14, s4
	v_cmpx_lt_u32_e64 s[10:11], s26, v25
	s_nop 1
	s_lshl_b32 s4, s14, 2
	v_mbcnt_lo_u32_b32 v27, s10, 0
	s_add_i32 s4, s96, s4
	v_mbcnt_hi_u32_b32 v27, s11, v27
	v_add_u32_e32 v26, 0x1a00, v33
	v_lshl_add_u32 v27, v27, 2, s4
	ds_write_b32 v27, v26
.LBB0_1519:
	s_mov_b64 exec, -1
	v_cmp_eq_u32_e32 vcc, s26, v25
	s_cbranch_vccz .LBB0_1523
	s_nop 0
	v_mbcnt_lo_u32_b32 v25, vcc_lo, 0
	v_mbcnt_hi_u32_b32 v25, vcc_hi, v25
	v_add_u32_e32 v25, s27, v25
	v_cmp_gt_i32_e64 s[12:13], s78, v25
	s_and_b64 s[4:5], vcc, s[12:13]
	s_and_saveexec_b64 s[12:13], s[4:5]
	v_add_u32_e32 v26, 0x1a00, v33
	v_lshl_add_u32 v25, v25, 2, s96
	ds_write_b32 v25, v26
	s_or_b64 exec, exec, s[12:13]
	s_bcnt1_i32_b64 s4, vcc
	s_add_i32 s27, s27, s4
.LBB0_1523:
	s_bcnt1_i32_b64 s4, s[10:11]
	s_add_i32 s14, s14, s4
	v_cmpx_lt_u32_e64 s[10:11], s26, v24
	s_nop 1
	s_lshl_b32 s4, s14, 2
	v_mbcnt_lo_u32_b32 v26, s10, 0
	s_add_i32 s4, s96, s4
	v_mbcnt_hi_u32_b32 v26, s11, v26
	v_add_u32_e32 v25, 0x1a40, v33
	v_lshl_add_u32 v26, v26, 2, s4
	ds_write_b32 v26, v25
.LBB0_1525:
	s_mov_b64 exec, -1
	v_cmp_eq_u32_e32 vcc, s26, v24
	s_cbranch_vccz .LBB0_1529
	s_nop 0
	v_mbcnt_lo_u32_b32 v24, vcc_lo, 0
	v_mbcnt_hi_u32_b32 v24, vcc_hi, v24
	v_add_u32_e32 v24, s27, v24
	v_cmp_gt_i32_e64 s[12:13], s78, v24
	s_and_b64 s[4:5], vcc, s[12:13]
	s_and_saveexec_b64 s[12:13], s[4:5]
	v_add_u32_e32 v25, 0x1a40, v33
	v_lshl_add_u32 v24, v24, 2, s96
	ds_write_b32 v24, v25
	s_or_b64 exec, exec, s[12:13]
	s_bcnt1_i32_b64 s4, vcc
	s_add_i32 s27, s27, s4
.LBB0_1529:
	s_bcnt1_i32_b64 s4, s[10:11]
	s_add_i32 s14, s14, s4
	v_cmpx_lt_u32_e64 s[10:11], s26, v23
	s_nop 1
	s_lshl_b32 s4, s14, 2
	v_mbcnt_lo_u32_b32 v25, s10, 0
	s_add_i32 s4, s96, s4
	v_mbcnt_hi_u32_b32 v25, s11, v25
	v_add_u32_e32 v24, 0x1a80, v33
	v_lshl_add_u32 v25, v25, 2, s4
	ds_write_b32 v25, v24
.LBB0_1531:
	s_mov_b64 exec, -1
	v_cmp_eq_u32_e32 vcc, s26, v23
	s_cbranch_vccz .LBB0_1535
	s_nop 0
	v_mbcnt_lo_u32_b32 v23, vcc_lo, 0
	v_mbcnt_hi_u32_b32 v23, vcc_hi, v23
	v_add_u32_e32 v23, s27, v23
	v_cmp_gt_i32_e64 s[12:13], s78, v23
	s_and_b64 s[4:5], vcc, s[12:13]
	s_and_saveexec_b64 s[12:13], s[4:5]
	v_add_u32_e32 v24, 0x1a80, v33
	v_lshl_add_u32 v23, v23, 2, s96
	ds_write_b32 v23, v24
	s_or_b64 exec, exec, s[12:13]
	s_bcnt1_i32_b64 s4, vcc
	s_add_i32 s27, s27, s4
.LBB0_1535:
	s_bcnt1_i32_b64 s4, s[10:11]
	s_add_i32 s14, s14, s4
	v_cmpx_lt_u32_e64 s[10:11], s26, v22
	s_nop 1
	s_lshl_b32 s4, s14, 2
	v_mbcnt_lo_u32_b32 v24, s10, 0
	s_add_i32 s4, s96, s4
	v_mbcnt_hi_u32_b32 v24, s11, v24
	v_add_u32_e32 v23, 0x1ac0, v33
	v_lshl_add_u32 v24, v24, 2, s4
	ds_write_b32 v24, v23
.LBB0_1537:
	s_mov_b64 exec, -1
	v_cmp_eq_u32_e32 vcc, s26, v22
	s_cbranch_vccz .LBB0_1541
	s_nop 0
	v_mbcnt_lo_u32_b32 v22, vcc_lo, 0
	v_mbcnt_hi_u32_b32 v22, vcc_hi, v22
	v_add_u32_e32 v22, s27, v22
	v_cmp_gt_i32_e64 s[12:13], s78, v22
	s_and_b64 s[4:5], vcc, s[12:13]
	s_and_saveexec_b64 s[12:13], s[4:5]
	v_add_u32_e32 v23, 0x1ac0, v33
	v_lshl_add_u32 v22, v22, 2, s96
	ds_write_b32 v22, v23
	s_or_b64 exec, exec, s[12:13]
	s_bcnt1_i32_b64 s4, vcc
	s_add_i32 s27, s27, s4
.LBB0_1541:
	s_bcnt1_i32_b64 s4, s[10:11]
	s_add_i32 s14, s14, s4
	v_cmpx_lt_u32_e64 s[10:11], s26, v21
	s_nop 1
	s_lshl_b32 s4, s14, 2
	v_mbcnt_lo_u32_b32 v23, s10, 0
	s_add_i32 s4, s96, s4
	v_mbcnt_hi_u32_b32 v23, s11, v23
	v_add_u32_e32 v22, 0x1b00, v33
	v_lshl_add_u32 v23, v23, 2, s4
	ds_write_b32 v23, v22
.LBB0_1543:
	s_mov_b64 exec, -1
	v_cmp_eq_u32_e32 vcc, s26, v21
	s_cbranch_vccz .LBB0_1547
	s_nop 0
	v_mbcnt_lo_u32_b32 v21, vcc_lo, 0
	v_mbcnt_hi_u32_b32 v21, vcc_hi, v21
	v_add_u32_e32 v21, s27, v21
	v_cmp_gt_i32_e64 s[12:13], s78, v21
	s_and_b64 s[4:5], vcc, s[12:13]
	s_and_saveexec_b64 s[12:13], s[4:5]
	v_add_u32_e32 v22, 0x1b00, v33
	v_lshl_add_u32 v21, v21, 2, s96
	ds_write_b32 v21, v22
	s_or_b64 exec, exec, s[12:13]
	s_bcnt1_i32_b64 s4, vcc
	s_add_i32 s27, s27, s4
.LBB0_1547:
	s_bcnt1_i32_b64 s4, s[10:11]
	s_add_i32 s14, s14, s4
	v_cmpx_lt_u32_e64 s[10:11], s26, v20
	s_nop 1
	s_lshl_b32 s4, s14, 2
	v_mbcnt_lo_u32_b32 v22, s10, 0
	s_add_i32 s4, s96, s4
	v_mbcnt_hi_u32_b32 v22, s11, v22
	v_add_u32_e32 v21, 0x1b40, v33
	v_lshl_add_u32 v22, v22, 2, s4
	ds_write_b32 v22, v21
.LBB0_1549:
	s_mov_b64 exec, -1
	v_cmp_eq_u32_e32 vcc, s26, v20
	s_cbranch_vccz .LBB0_1553
	s_nop 0
	v_mbcnt_lo_u32_b32 v20, vcc_lo, 0
	v_mbcnt_hi_u32_b32 v20, vcc_hi, v20
	v_add_u32_e32 v20, s27, v20
	v_cmp_gt_i32_e64 s[12:13], s78, v20
	s_and_b64 s[4:5], vcc, s[12:13]
	s_and_saveexec_b64 s[12:13], s[4:5]
	v_add_u32_e32 v21, 0x1b40, v33
	v_lshl_add_u32 v20, v20, 2, s96
	ds_write_b32 v20, v21
	s_or_b64 exec, exec, s[12:13]
	s_bcnt1_i32_b64 s4, vcc
	s_add_i32 s27, s27, s4
.LBB0_1553:
	s_bcnt1_i32_b64 s4, s[10:11]
	s_add_i32 s14, s14, s4
	v_cmpx_lt_u32_e64 s[10:11], s26, v19
	s_nop 1
	s_lshl_b32 s4, s14, 2
	v_mbcnt_lo_u32_b32 v21, s10, 0
	s_add_i32 s4, s96, s4
	v_mbcnt_hi_u32_b32 v21, s11, v21
	v_add_u32_e32 v20, 0x1b80, v33
	v_lshl_add_u32 v21, v21, 2, s4
	ds_write_b32 v21, v20
.LBB0_1555:
	s_mov_b64 exec, -1
	v_cmp_eq_u32_e32 vcc, s26, v19
	s_cbranch_vccz .LBB0_1559
	s_nop 0
	v_mbcnt_lo_u32_b32 v19, vcc_lo, 0
	v_mbcnt_hi_u32_b32 v19, vcc_hi, v19
	v_add_u32_e32 v19, s27, v19
	v_cmp_gt_i32_e64 s[12:13], s78, v19
	s_and_b64 s[4:5], vcc, s[12:13]
	s_and_saveexec_b64 s[12:13], s[4:5]
	v_add_u32_e32 v20, 0x1b80, v33
	v_lshl_add_u32 v19, v19, 2, s96
	ds_write_b32 v19, v20
	s_or_b64 exec, exec, s[12:13]
	s_bcnt1_i32_b64 s4, vcc
	s_add_i32 s27, s27, s4
.LBB0_1559:
	s_bcnt1_i32_b64 s4, s[10:11]
	s_add_i32 s14, s14, s4
	v_cmpx_lt_u32_e64 s[10:11], s26, v15
	s_nop 1
	s_lshl_b32 s4, s14, 2
	v_mbcnt_lo_u32_b32 v20, s10, 0
	s_add_i32 s4, s96, s4
	v_mbcnt_hi_u32_b32 v20, s11, v20
	v_add_u32_e32 v19, 0x1bc0, v33
	v_lshl_add_u32 v20, v20, 2, s4
	ds_write_b32 v20, v19
.LBB0_1561:
	s_mov_b64 exec, -1
	v_cmp_eq_u32_e32 vcc, s26, v15
	s_cbranch_vccz .LBB0_1565
	s_nop 0
	v_mbcnt_lo_u32_b32 v15, vcc_lo, 0
	v_mbcnt_hi_u32_b32 v15, vcc_hi, v15
	v_add_u32_e32 v15, s27, v15
	v_cmp_gt_i32_e64 s[12:13], s78, v15
	s_and_b64 s[4:5], vcc, s[12:13]
	s_and_saveexec_b64 s[12:13], s[4:5]
	v_add_u32_e32 v19, 0x1bc0, v33
	v_lshl_add_u32 v15, v15, 2, s96
	ds_write_b32 v15, v19
	s_or_b64 exec, exec, s[12:13]
	s_bcnt1_i32_b64 s4, vcc
	s_add_i32 s27, s27, s4

; __device__ __forceinline__ void dsa_tile(const Params& p, unsigned char* smem, int tile) {
;     ...
;                     for (int r = g * 16; r < g * 16 + 16; ++r) {
;                         const bool sel = uu[r] > tau;
;                         const unsigned long long mk = __ballot(sel);
;                         const int pos = base + __builtin_amdgcn_mbcnt_hi((unsigned)(mk >> 32), __builtin_amdgcn_mbcnt_lo((unsigned)mk, 0));
;                         if (sel) myidx[pos] = r * 64 + lo;
;                         base += __popcll(mk);
;                         const unsigned long long me = __ballot(uu[r] == tau);
;                         if (me != 0ull) {
;                             const int epos = ebase + __builtin_amdgcn_mbcnt_hi((unsigned)(me >> 32), __builtin_amdgcn_mbcnt_lo((unsigned)me, 0));
;                             if (uu[r] == tau && epos < 256) myidx[epos] = r * 64 + lo;
;                             ebase += __popcll(me);
;                         }
.LBB0_1572:
	s_bcnt1_i32_b64 s4, s[8:9]
	s_add_i32 s12, s24, s4
	v_cmpx_lt_u32_e64 s[8:9], s26, v17
	s_nop 1
	s_lshl_b32 s4, s12, 2
	v_mbcnt_lo_u32_b32 v19, s8, 0
	s_add_i32 s4, s96, s4
	v_mbcnt_hi_u32_b32 v19, s9, v19
	v_add_u32_e32 v18, 0x1c40, v15
	v_lshl_add_u32 v19, v19, 2, s4
	ds_write_b32 v19, v18
.LBB0_1574:
	s_mov_b64 exec, -1
	v_cmp_eq_u32_e32 vcc, s26, v17
	s_cbranch_vccz .LBB0_1578
	s_nop 0
	v_mbcnt_lo_u32_b32 v17, vcc_lo, 0
	v_mbcnt_hi_u32_b32 v17, vcc_hi, v17
	v_add_u32_e32 v17, s27, v17
	v_cmp_gt_i32_e64 s[10:11], s78, v17
	s_and_b64 s[4:5], vcc, s[10:11]
	s_and_saveexec_b64 s[10:11], s[4:5]
	v_add_u32_e32 v18, 0x1c40, v15
	v_lshl_add_u32 v17, v17, 2, s96
	ds_write_b32 v17, v18
	s_or_b64 exec, exec, s[10:11]
	s_bcnt1_i32_b64 s4, vcc
	s_add_i32 s27, s27, s4
.LBB0_1578:
	s_bcnt1_i32_b64 s4, s[8:9]
	s_add_i32 s12, s12, s4
	v_cmpx_lt_u32_e64 s[8:9], s26, v16
	s_nop 1
	s_lshl_b32 s4, s12, 2
	v_mbcnt_lo_u32_b32 v18, s8, 0
	s_add_i32 s4, s96, s4
	v_mbcnt_hi_u32_b32 v18, s9, v18
	v_add_u32_e32 v17, 0x1c80, v15
	v_lshl_add_u32 v18, v18, 2, s4
	ds_write_b32 v18, v17
.LBB0_1580:
	s_mov_b64 exec, -1
	v_cmp_eq_u32_e32 vcc, s26, v16
	s_cbranch_vccz .LBB0_1584
	s_nop 0
	v_mbcnt_lo_u32_b32 v16, vcc_lo, 0
	v_mbcnt_hi_u32_b32 v16, vcc_hi, v16
	v_add_u32_e32 v16, s27, v16
	v_cmp_gt_i32_e64 s[10:11], s78, v16
	s_and_b64 s[4:5], vcc, s[10:11]
	s_and_saveexec_b64 s[10:11], s[4:5]
	v_add_u32_e32 v17, 0x1c80, v15
	v_lshl_add_u32 v16, v16, 2, s96
	ds_write_b32 v16, v17
	s_or_b64 exec, exec, s[10:11]
	s_bcnt1_i32_b64 s4, vcc
	s_add_i32 s27, s27, s4
.LBB0_1584:
	s_bcnt1_i32_b64 s4, s[8:9]
	s_add_i32 s12, s12, s4
	v_cmpx_lt_u32_e64 s[8:9], s26, v14
	s_nop 1
	s_lshl_b32 s4, s12, 2
	v_mbcnt_lo_u32_b32 v17, s8, 0
	s_add_i32 s4, s96, s4
	v_mbcnt_hi_u32_b32 v17, s9, v17
	v_add_u32_e32 v16, 0x1cc0, v15
	v_lshl_add_u32 v17, v17, 2, s4
	ds_write_b32 v17, v16
.LBB0_1586:
	s_mov_b64 exec, -1
	v_cmp_eq_u32_e32 vcc, s26, v14
	s_cbranch_vccz .LBB0_1590
	s_nop 0
	v_mbcnt_lo_u32_b32 v14, vcc_lo, 0
	v_mbcnt_hi_u32_b32 v14, vcc_hi, v14
	v_add_u32_e32 v14, s27, v14
	v_cmp_gt_i32_e64 s[10:11], s78, v14
	s_and_b64 s[4:5], vcc, s[10:11]
	s_and_saveexec_b64 s[10:11], s[4:5]
	v_add_u32_e32 v16, 0x1cc0, v15
	v_lshl_add_u32 v14, v14, 2, s96
	ds_write_b32 v14, v16
	s_or_b64 exec, exec, s[10:11]
	s_bcnt1_i32_b64 s4, vcc
	s_add_i32 s27, s27, s4
.LBB0_1590:
	s_bcnt1_i32_b64 s4, s[8:9]
	s_add_i32 s12, s12, s4
	v_cmpx_lt_u32_e64 s[8:9], s26, v13
	s_nop 1
	s_lshl_b32 s4, s12, 2
	v_mbcnt_lo_u32_b32 v16, s8, 0
	s_add_i32 s4, s96, s4
	v_mbcnt_hi_u32_b32 v16, s9, v16
	v_add_u32_e32 v14, 0x1d00, v15
	v_lshl_add_u32 v16, v16, 2, s4
	ds_write_b32 v16, v14
.LBB0_1592:
	s_mov_b64 exec, -1
	v_cmp_eq_u32_e32 vcc, s26, v13
	s_cbranch_vccz .LBB0_1596
	s_nop 0
	v_mbcnt_lo_u32_b32 v13, vcc_lo, 0
	v_mbcnt_hi_u32_b32 v13, vcc_hi, v13
	v_add_u32_e32 v13, s27, v13
	v_cmp_gt_i32_e64 s[10:11], s78, v13
	s_and_b64 s[4:5], vcc, s[10:11]
	s_and_saveexec_b64 s[10:11], s[4:5]
	v_add_u32_e32 v14, 0x1d00, v15
	v_lshl_add_u32 v13, v13, 2, s96
	ds_write_b32 v13, v14
	s_or_b64 exec, exec, s[10:11]
	s_bcnt1_i32_b64 s4, vcc
	s_add_i32 s27, s27, s4
.LBB0_1596:
	s_bcnt1_i32_b64 s4, s[8:9]
	s_add_i32 s12, s12, s4
	v_cmpx_lt_u32_e64 s[8:9], s26, v12
	s_nop 1
	s_lshl_b32 s4, s12, 2
	v_mbcnt_lo_u32_b32 v14, s8, 0
	s_add_i32 s4, s96, s4
	v_mbcnt_hi_u32_b32 v14, s9, v14
	v_add_u32_e32 v13, 0x1d40, v15
	v_lshl_add_u32 v14, v14, 2, s4
	ds_write_b32 v14, v13
.LBB0_1598:
	s_mov_b64 exec, -1
	v_cmp_eq_u32_e32 vcc, s26, v12
	s_cbranch_vccz .LBB0_1602
	s_nop 0
	v_mbcnt_lo_u32_b32 v12, vcc_lo, 0
	v_mbcnt_hi_u32_b32 v12, vcc_hi, v12
	v_add_u32_e32 v12, s27, v12
	v_cmp_gt_i32_e64 s[10:11], s78, v12
	s_and_b64 s[4:5], vcc, s[10:11]
	s_and_saveexec_b64 s[10:11], s[4:5]
	v_add_u32_e32 v13, 0x1d40, v15
	v_lshl_add_u32 v12, v12, 2, s96
	ds_write_b32 v12, v13
	s_or_b64 exec, exec, s[10:11]
	s_bcnt1_i32_b64 s4, vcc
	s_add_i32 s27, s27, s4
.LBB0_1602:
	s_bcnt1_i32_b64 s4, s[8:9]
	s_add_i32 s12, s12, s4
	v_cmpx_lt_u32_e64 s[8:9], s26, v11
	s_nop 1
	s_lshl_b32 s4, s12, 2
	v_mbcnt_lo_u32_b32 v13, s8, 0
	s_add_i32 s4, s96, s4
	v_mbcnt_hi_u32_b32 v13, s9, v13
	v_add_u32_e32 v12, 0x1d80, v15
	v_lshl_add_u32 v13, v13, 2, s4
	ds_write_b32 v13, v12
.LBB0_1604:
	s_mov_b64 exec, -1
	v_cmp_eq_u32_e32 vcc, s26, v11
	s_cbranch_vccz .LBB0_1608
	s_nop 0
	v_mbcnt_lo_u32_b32 v11, vcc_lo, 0
	v_mbcnt_hi_u32_b32 v11, vcc_hi, v11
	v_add_u32_e32 v11, s27, v11
	v_cmp_gt_i32_e64 s[10:11], s78, v11
	s_and_b64 s[4:5], vcc, s[10:11]
	s_and_saveexec_b64 s[10:11], s[4:5]
	v_add_u32_e32 v12, 0x1d80, v15
	v_lshl_add_u32 v11, v11, 2, s96
	ds_write_b32 v11, v12
	s_or_b64 exec, exec, s[10:11]
	s_bcnt1_i32_b64 s4, vcc
	s_add_i32 s27, s27, s4
.LBB0_1608:
	s_bcnt1_i32_b64 s4, s[8:9]
	s_add_i32 s12, s12, s4
	v_cmpx_lt_u32_e64 s[8:9], s26, v10
	s_nop 1
	s_lshl_b32 s4, s12, 2
	v_mbcnt_lo_u32_b32 v12, s8, 0
	s_add_i32 s4, s96, s4
	v_mbcnt_hi_u32_b32 v12, s9, v12
	v_add_u32_e32 v11, 0x1dc0, v15
	v_lshl_add_u32 v12, v12, 2, s4
	ds_write_b32 v12, v11
.LBB0_1610:
	s_mov_b64 exec, -1
	v_cmp_eq_u32_e32 vcc, s26, v10
	s_cbranch_vccz .LBB0_1614
	s_nop 0
	v_mbcnt_lo_u32_b32 v10, vcc_lo, 0
	v_mbcnt_hi_u32_b32 v10, vcc_hi, v10
	v_add_u32_e32 v10, s27, v10
	v_cmp_gt_i32_e64 s[10:11], s78, v10
	s_and_b64 s[4:5], vcc, s[10:11]
	s_and_saveexec_b64 s[10:11], s[4:5]
	v_add_u32_e32 v11, 0x1dc0, v15
	v_lshl_add_u32 v10, v10, 2, s96
	ds_write_b32 v10, v11
	s_or_b64 exec, exec, s[10:11]
	s_bcnt1_i32_b64 s4, vcc
	s_add_i32 s27, s27, s4
; __device__ __forceinline__ void dsa_tile(const Params& p, unsigned char* smem, int tile) {
;     ...
;                     for (int r = g * 16; r < g * 16 + 16; ++r) {
;                         const bool sel = uu[r] > tau;
;                         const unsigned long long mk = __ballot(sel);
;                         const int pos = base + __builtin_amdgcn_mbcnt_hi((unsigned)(mk >> 32), __builtin_amdgcn_mbcnt_lo((unsigned)mk, 0));
;                         if (sel) myidx[pos] = r * 64 + lo;
;                         base += __popcll(mk);
;                         const unsigned long long me = __ballot(uu[r] == tau);
;                         if (me != 0ull) {
;                             const int epos = ebase + __builtin_amdgcn_mbcnt_hi((unsigned)(me >> 32), __builtin_amdgcn_mbcnt_lo((unsigned)me, 0));
;                             if (uu[r] == tau && epos < 256) myidx[epos] = r * 64 + lo;
;                             ebase += __popcll(me);
;                         }
.LBB0_1614:
	s_bcnt1_i32_b64 s4, s[8:9]
	s_add_i32 s12, s12, s4
	v_cmpx_lt_u32_e64 s[8:9], s26, v9
	s_nop 1
	s_lshl_b32 s4, s12, 2
	v_mbcnt_lo_u32_b32 v11, s8, 0
	s_add_i32 s4, s96, s4
	v_mbcnt_hi_u32_b32 v11, s9, v11
	v_add_u32_e32 v10, 0x1e00, v15
	v_lshl_add_u32 v11, v11, 2, s4
	ds_write_b32 v11, v10
.LBB0_1616:
	s_mov_b64 exec, -1
	v_cmp_eq_u32_e32 vcc, s26, v9
	s_cbranch_vccz .LBB0_1620
	s_nop 0
	v_mbcnt_lo_u32_b32 v9, vcc_lo, 0
	v_mbcnt_hi_u32_b32 v9, vcc_hi, v9
	v_add_u32_e32 v9, s27, v9
	v_cmp_gt_i32_e64 s[10:11], s78, v9
	s_and_b64 s[4:5], vcc, s[10:11]
	s_and_saveexec_b64 s[10:11], s[4:5]
	v_add_u32_e32 v10, 0x1e00, v15
	v_lshl_add_u32 v9, v9, 2, s96
	ds_write_b32 v9, v10
	s_or_b64 exec, exec, s[10:11]
	s_bcnt1_i32_b64 s4, vcc
	s_add_i32 s27, s27, s4
.LBB0_1620:
	s_bcnt1_i32_b64 s4, s[8:9]
	s_add_i32 s12, s12, s4
	v_cmpx_lt_u32_e64 s[8:9], s26, v8
	s_nop 1
	s_lshl_b32 s4, s12, 2
	v_mbcnt_lo_u32_b32 v10, s8, 0
	s_add_i32 s4, s96, s4
	v_mbcnt_hi_u32_b32 v10, s9, v10
	v_add_u32_e32 v9, 0x1e40, v15
	v_lshl_add_u32 v10, v10, 2, s4
	ds_write_b32 v10, v9
.LBB0_1622:
	s_mov_b64 exec, -1
	v_cmp_eq_u32_e32 vcc, s26, v8
	s_cbranch_vccz .LBB0_1626
	s_nop 0
	v_mbcnt_lo_u32_b32 v8, vcc_lo, 0
	v_mbcnt_hi_u32_b32 v8, vcc_hi, v8
	v_add_u32_e32 v8, s27, v8
	v_cmp_gt_i32_e64 s[10:11], s78, v8
	s_and_b64 s[4:5], vcc, s[10:11]
	s_and_saveexec_b64 s[10:11], s[4:5]
	v_add_u32_e32 v9, 0x1e40, v15
	v_lshl_add_u32 v8, v8, 2, s96
	ds_write_b32 v8, v9
	s_or_b64 exec, exec, s[10:11]
	s_bcnt1_i32_b64 s4, vcc
	s_add_i32 s27, s27, s4
.LBB0_1626:
	s_bcnt1_i32_b64 s4, s[8:9]
	s_add_i32 s12, s12, s4
	v_cmpx_lt_u32_e64 s[8:9], s26, v7
	s_nop 1
	s_lshl_b32 s4, s12, 2
	v_mbcnt_lo_u32_b32 v9, s8, 0
	s_add_i32 s4, s96, s4
	v_mbcnt_hi_u32_b32 v9, s9, v9
	v_add_u32_e32 v8, 0x1e80, v15
	v_lshl_add_u32 v9, v9, 2, s4
	ds_write_b32 v9, v8
.LBB0_1628:
	s_mov_b64 exec, -1
	v_cmp_eq_u32_e32 vcc, s26, v7
	s_cbranch_vccz .LBB0_1632
	s_nop 0
	v_mbcnt_lo_u32_b32 v7, vcc_lo, 0
	v_mbcnt_hi_u32_b32 v7, vcc_hi, v7
	v_add_u32_e32 v7, s27, v7
	v_cmp_gt_i32_e64 s[10:11], s78, v7
	s_and_b64 s[4:5], vcc, s[10:11]
	s_and_saveexec_b64 s[10:11], s[4:5]
	v_add_u32_e32 v8, 0x1e80, v15
	v_lshl_add_u32 v7, v7, 2, s96
	ds_write_b32 v7, v8
	s_or_b64 exec, exec, s[10:11]
	s_bcnt1_i32_b64 s4, vcc
	s_add_i32 s27, s27, s4
.LBB0_1632:
	s_bcnt1_i32_b64 s4, s[8:9]
	s_add_i32 s12, s12, s4
	v_cmpx_lt_u32_e64 s[8:9], s26, v6
	s_nop 1
	s_lshl_b32 s4, s12, 2
	v_mbcnt_lo_u32_b32 v8, s8, 0
	s_add_i32 s4, s96, s4
	v_mbcnt_hi_u32_b32 v8, s9, v8
	v_add_u32_e32 v7, 0x1ec0, v15
	v_lshl_add_u32 v8, v8, 2, s4
	ds_write_b32 v8, v7
.LBB0_1634:
	s_mov_b64 exec, -1
	v_cmp_eq_u32_e32 vcc, s26, v6
	s_cbranch_vccz .LBB0_1638
	s_nop 0
	v_mbcnt_lo_u32_b32 v6, vcc_lo, 0
	v_mbcnt_hi_u32_b32 v6, vcc_hi, v6
	v_add_u32_e32 v6, s27, v6
	v_cmp_gt_i32_e64 s[10:11], s78, v6
	s_and_b64 s[4:5], vcc, s[10:11]
	s_and_saveexec_b64 s[10:11], s[4:5]
	v_add_u32_e32 v7, 0x1ec0, v15
	v_lshl_add_u32 v6, v6, 2, s96
	ds_write_b32 v6, v7
	s_or_b64 exec, exec, s[10:11]
	s_bcnt1_i32_b64 s4, vcc
	s_add_i32 s27, s27, s4
.LBB0_1638:
	s_bcnt1_i32_b64 s4, s[8:9]
	s_add_i32 s12, s12, s4
	v_cmpx_lt_u32_e64 s[8:9], s26, v5
	s_nop 1
	s_lshl_b32 s4, s12, 2
	v_mbcnt_lo_u32_b32 v7, s8, 0
	s_add_i32 s4, s96, s4
	v_mbcnt_hi_u32_b32 v7, s9, v7
	v_add_u32_e32 v6, 0x1f00, v15
	v_lshl_add_u32 v7, v7, 2, s4
	ds_write_b32 v7, v6
.LBB0_1640:
	s_mov_b64 exec, -1
	v_cmp_eq_u32_e32 vcc, s26, v5
	s_cbranch_vccz .LBB0_1644
	s_nop 0
	v_mbcnt_lo_u32_b32 v5, vcc_lo, 0
	v_mbcnt_hi_u32_b32 v5, vcc_hi, v5
	v_add_u32_e32 v5, s27, v5
	v_cmp_gt_i32_e64 s[10:11], s78, v5
	s_and_b64 s[4:5], vcc, s[10:11]
	s_and_saveexec_b64 s[10:11], s[4:5]
	v_add_u32_e32 v6, 0x1f00, v15
	v_lshl_add_u32 v5, v5, 2, s96
	ds_write_b32 v5, v6
	s_or_b64 exec, exec, s[10:11]
	s_bcnt1_i32_b64 s4, vcc
	s_add_i32 s27, s27, s4
.LBB0_1644:
	s_bcnt1_i32_b64 s4, s[8:9]
	s_add_i32 s12, s12, s4
	v_cmpx_lt_u32_e64 s[8:9], s26, v4
	s_nop 1
	s_lshl_b32 s4, s12, 2
	v_mbcnt_lo_u32_b32 v6, s8, 0
	s_add_i32 s4, s96, s4
	v_mbcnt_hi_u32_b32 v6, s9, v6
	v_add_u32_e32 v5, 0x1f40, v15
	v_lshl_add_u32 v6, v6, 2, s4
	ds_write_b32 v6, v5
.LBB0_1646:
	s_mov_b64 exec, -1
	v_cmp_eq_u32_e32 vcc, s26, v4
	s_cbranch_vccz .LBB0_1650
	s_nop 0
	v_mbcnt_lo_u32_b32 v4, vcc_lo, 0
	v_mbcnt_hi_u32_b32 v4, vcc_hi, v4
	v_add_u32_e32 v4, s27, v4
	v_cmp_gt_i32_e64 s[10:11], s78, v4
	s_and_b64 s[4:5], vcc, s[10:11]
	s_and_saveexec_b64 s[10:11], s[4:5]
	v_add_u32_e32 v5, 0x1f40, v15
	v_lshl_add_u32 v4, v4, 2, s96
	ds_write_b32 v4, v5
	s_or_b64 exec, exec, s[10:11]
	s_bcnt1_i32_b64 s4, vcc
	s_add_i32 s27, s27, s4
.LBB0_1650:
	s_bcnt1_i32_b64 s4, s[8:9]
	s_add_i32 s12, s12, s4
	v_cmpx_lt_u32_e64 s[8:9], s26, v3
	s_nop 1
	s_lshl_b32 s4, s12, 2
	v_mbcnt_lo_u32_b32 v5, s8, 0
	s_add_i32 s4, s96, s4
	v_mbcnt_hi_u32_b32 v5, s9, v5
	v_add_u32_e32 v4, 0x1f80, v15
	v_lshl_add_u32 v5, v5, 2, s4
	ds_write_b32 v5, v4
.LBB0_1652:
	s_mov_b64 exec, -1
	v_cmp_eq_u32_e32 vcc, s26, v3
	s_cbranch_vccz .LBB0_1656
	s_nop 0
	v_mbcnt_lo_u32_b32 v3, vcc_lo, 0
	v_mbcnt_hi_u32_b32 v3, vcc_hi, v3
	v_add_u32_e32 v3, s27, v3
	v_cmp_gt_i32_e64 s[10:11], s78, v3
	s_and_b64 s[4:5], vcc, s[10:11]
	s_and_saveexec_b64 s[10:11], s[4:5]
	v_add_u32_e32 v4, 0x1f80, v15
	v_lshl_add_u32 v3, v3, 2, s96
	ds_write_b32 v3, v4
	s_or_b64 exec, exec, s[10:11]
	s_bcnt1_i32_b64 s4, vcc
	s_add_i32 s27, s27, s4
